# K-loop DMA loads split: four after the barrier in the fourth MFMA group, four in the first group of the next step; plus batched Q/K stage-in in the retention chunk unit
# speedup vs baseline: 1.0592x; 1.0082x over previous
.LBB0_150:
	s_and_b32 s27, s37, 0x10000
	s_xor_b32 s38, s27, 0x10000
	s_add_i32 s27, s27, 0
	s_add_i32 s101, s100, s38
	s_waitcnt lgkmcnt(3)
	v_mfma_f32_16x16x32_bf16 v[124:127], v[160:163], v[180:183], v[124:127]
	v_mfma_f32_16x16x32_bf16 v[108:111], v[168:171], v[180:183], v[108:111]
	v_mfma_f32_16x16x32_bf16 v[92:95], v[172:175], v[180:183], v[92:95]
	v_mfma_f32_16x16x32_bf16 v[76:79], v[176:179], v[180:183], v[76:79]
	ds_read_b128 v[240:243], v200
	ds_read_b128 v[244:247], v201
	s_cmpk_eq_i32 s4, 0
	s_cbranch_scc1 .Lpk_150_4
	s_add_i32 m0, s101, 0x4000
	v_lshl_add_u64 v[142:143], v[142:143], 0, s[98:99]
	global_load_lds_dwordx4 v[142:143], off
.Lpk_150_4:
	s_waitcnt lgkmcnt(4)
	v_mfma_f32_16x16x32_bf16 v[120:123], v[160:163], v[184:187], v[120:123]
	v_mfma_f32_16x16x32_bf16 v[104:107], v[168:171], v[184:187], v[104:107]
	v_mfma_f32_16x16x32_bf16 v[88:91], v[172:175], v[184:187], v[88:91]
	v_mfma_f32_16x16x32_bf16 v[72:75], v[176:179], v[184:187], v[72:75]
	ds_read_b128 v[248:251], v202
	ds_read_b128 v[252:255], v203
	s_cmpk_eq_i32 s4, 0
	s_cbranch_scc1 .Lpk_150_5
	s_add_i32 m0, s101, 0xc000
	v_lshl_add_u64 v[130:131], v[130:131], 0, s[98:99]
	global_load_lds_dwordx4 v[130:131], off
.Lpk_150_5:
	s_waitcnt lgkmcnt(5)
	v_mfma_f32_16x16x32_bf16 v[116:119], v[160:163], v[188:191], v[116:119]
	v_mfma_f32_16x16x32_bf16 v[100:103], v[168:171], v[188:191], v[100:103]
	v_mfma_f32_16x16x32_bf16 v[84:87], v[172:175], v[188:191], v[84:87]
	v_mfma_f32_16x16x32_bf16 v[68:71], v[176:179], v[188:191], v[68:71]
	s_cmpk_eq_i32 s4, 0
	s_cbranch_scc1 .Lpk_150_6
	s_add_i32 m0, s101, 0x6000
	v_lshl_add_u64 v[140:141], v[140:141], 0, s[98:99]
	global_load_lds_dwordx4 v[140:141], off
.Lpk_150_6:
	s_waitcnt lgkmcnt(4)
	v_mfma_f32_16x16x32_bf16 v[112:115], v[160:163], v[192:195], v[112:115]
	v_mfma_f32_16x16x32_bf16 v[96:99], v[168:171], v[192:195], v[96:99]
	v_mfma_f32_16x16x32_bf16 v[80:83], v[172:175], v[192:195], v[80:83]
	v_mfma_f32_16x16x32_bf16 v[64:67], v[176:179], v[192:195], v[64:67]
	s_cmpk_eq_i32 s4, 0
	s_cbranch_scc1 .Lpk_150_7
	s_add_i32 m0, s101, 0xe000
	v_lshl_add_u64 v[128:129], v[128:129], 0, s[98:99]
	global_load_lds_dwordx4 v[128:129], off
.Lpk_150_7:
	ds_read_b128 v[160:163], v196 offset:1024
	ds_read_b128 v[168:171], v197 offset:1024
	ds_read_b128 v[172:175], v198 offset:1024
	ds_read_b128 v[176:179], v199 offset:1024
	s_waitcnt lgkmcnt(4)
	v_mfma_f32_16x16x32_bf16 v[60:63], v[240:243], v[180:183], v[60:63]
	v_mfma_f32_16x16x32_bf16 v[44:47], v[244:247], v[180:183], v[44:47]
	v_mfma_f32_16x16x32_bf16 v[16:19], v[248:251], v[180:183], v[16:19]
	v_mfma_f32_16x16x32_bf16 v[36:39], v[252:255], v[180:183], v[36:39]
	ds_read_b128 v[180:183], v134 offset:33792
	v_mfma_f32_16x16x32_bf16 v[56:59], v[240:243], v[184:187], v[56:59]
	v_mfma_f32_16x16x32_bf16 v[40:43], v[244:247], v[184:187], v[40:43]
	v_mfma_f32_16x16x32_bf16 v[12:15], v[248:251], v[184:187], v[12:15]
	v_mfma_f32_16x16x32_bf16 v[28:31], v[252:255], v[184:187], v[28:31]
	ds_read_b128 v[184:187], v134 offset:35840
	v_mfma_f32_16x16x32_bf16 v[52:55], v[240:243], v[188:191], v[52:55]
	v_mfma_f32_16x16x32_bf16 v[32:35], v[244:247], v[188:191], v[32:35]
	v_mfma_f32_16x16x32_bf16 v[4:7], v[248:251], v[188:191], v[4:7]
	v_mfma_f32_16x16x32_bf16 v[20:23], v[252:255], v[188:191], v[20:23]
	ds_read_b128 v[188:191], v134 offset:37888
	v_mfma_f32_16x16x32_bf16 v[48:51], v[240:243], v[192:195], v[48:51]
	v_mfma_f32_16x16x32_bf16 v[24:27], v[244:247], v[192:195], v[24:27]
	v_mfma_f32_16x16x32_bf16 v[0:3], v[248:251], v[192:195], v[0:3]
	v_mfma_f32_16x16x32_bf16 v[8:11], v[252:255], v[192:195], v[8:11]
	ds_read_b128 v[192:195], v134 offset:39936
	s_waitcnt lgkmcnt(3)
	v_mfma_f32_16x16x32_bf16 v[124:127], v[160:163], v[180:183], v[124:127]
	v_mfma_f32_16x16x32_bf16 v[108:111], v[168:171], v[180:183], v[108:111]
	v_mfma_f32_16x16x32_bf16 v[92:95], v[172:175], v[180:183], v[92:95]
	v_mfma_f32_16x16x32_bf16 v[76:79], v[176:179], v[180:183], v[76:79]
	ds_read_b128 v[240:243], v200 offset:1024
	ds_read_b128 v[244:247], v201 offset:1024
	s_waitcnt lgkmcnt(4)
	v_mfma_f32_16x16x32_bf16 v[120:123], v[160:163], v[184:187], v[120:123]
	v_mfma_f32_16x16x32_bf16 v[104:107], v[168:171], v[184:187], v[104:107]
	v_mfma_f32_16x16x32_bf16 v[88:91], v[172:175], v[184:187], v[88:91]
	v_mfma_f32_16x16x32_bf16 v[72:75], v[176:179], v[184:187], v[72:75]
	ds_read_b128 v[248:251], v202 offset:1024
	ds_read_b128 v[252:255], v203 offset:1024
	s_waitcnt lgkmcnt(5)
	v_mfma_f32_16x16x32_bf16 v[116:119], v[160:163], v[188:191], v[116:119]
	v_mfma_f32_16x16x32_bf16 v[100:103], v[168:171], v[188:191], v[100:103]
	v_mfma_f32_16x16x32_bf16 v[84:87], v[172:175], v[188:191], v[84:87]
	v_mfma_f32_16x16x32_bf16 v[68:71], v[176:179], v[188:191], v[68:71]
	s_waitcnt lgkmcnt(4)
	v_mfma_f32_16x16x32_bf16 v[112:115], v[160:163], v[192:195], v[112:115]
	v_mfma_f32_16x16x32_bf16 v[96:99], v[168:171], v[192:195], v[96:99]
	v_mfma_f32_16x16x32_bf16 v[80:83], v[172:175], v[192:195], v[80:83]
	v_mfma_f32_16x16x32_bf16 v[64:67], v[176:179], v[192:195], v[64:67]
	s_waitcnt vmcnt(0) lgkmcnt(0)
	s_barrier
	s_add_i32 s101, s100, s27
	v_mfma_f32_16x16x32_bf16 v[60:63], v[240:243], v[180:183], v[60:63]
	v_mfma_f32_16x16x32_bf16 v[44:47], v[244:247], v[180:183], v[44:47]
	v_mfma_f32_16x16x32_bf16 v[16:19], v[248:251], v[180:183], v[16:19]
	v_mfma_f32_16x16x32_bf16 v[36:39], v[252:255], v[180:183], v[36:39]
	v_add3_u32 v134, s38, v149, v150
	ds_read_b128 v[180:183], v134 offset:32768
	v_add3_u32 v196, s38, v149, v151
	v_add3_u32 v197, s38, v153, v152
	v_add3_u32 v198, s38, v153, v154
	v_add3_u32 v199, s38, v153, v155
	ds_read_b128 v[160:163], v196
	ds_read_b128 v[168:171], v197
	ds_read_b128 v[172:175], v198
	ds_read_b128 v[176:179], v199
	s_cmpk_eq_i32 s4, 0x700
	s_cbranch_scc1 .Lpk_150_0
	s_mov_b32 m0, s101
	v_lshl_add_u64 v[146:147], v[146:147], 0, s[98:99]
	global_load_lds_dwordx4 v[146:147], off
.Lpk_150_0:
	v_mfma_f32_16x16x32_bf16 v[56:59], v[240:243], v[184:187], v[56:59]
	v_mfma_f32_16x16x32_bf16 v[40:43], v[244:247], v[184:187], v[40:43]
	v_mfma_f32_16x16x32_bf16 v[12:15], v[248:251], v[184:187], v[12:15]
	v_mfma_f32_16x16x32_bf16 v[28:31], v[252:255], v[184:187], v[28:31]
	ds_read_b128 v[184:187], v134 offset:34816
	v_add3_u32 v200, s38, v153, v156
	v_add3_u32 v201, s38, v153, v157
	v_add3_u32 v202, s38, v153, v158
	v_add3_u32 v203, s38, v153, v159
	s_cmpk_eq_i32 s4, 0x700
	s_cbranch_scc1 .Lpk_150_1
	s_add_i32 m0, s101, 0x8000
	v_lshl_add_u64 v[138:139], v[138:139], 0, s[98:99]
	global_load_lds_dwordx4 v[138:139], off
.Lpk_150_1:
	v_mfma_f32_16x16x32_bf16 v[52:55], v[240:243], v[188:191], v[52:55]
	v_mfma_f32_16x16x32_bf16 v[32:35], v[244:247], v[188:191], v[32:35]
	v_mfma_f32_16x16x32_bf16 v[4:7], v[248:251], v[188:191], v[4:7]
	v_mfma_f32_16x16x32_bf16 v[20:23], v[252:255], v[188:191], v[20:23]
	ds_read_b128 v[188:191], v134 offset:36864
	s_cmpk_eq_i32 s4, 0x700
	s_cbranch_scc1 .Lpk_150_2
	s_add_i32 m0, s101, 0x2000
	v_lshl_add_u64 v[144:145], v[144:145], 0, s[98:99]
	global_load_lds_dwordx4 v[144:145], off
.Lpk_150_2:
	v_mfma_f32_16x16x32_bf16 v[48:51], v[240:243], v[192:195], v[48:51]
	v_mfma_f32_16x16x32_bf16 v[24:27], v[244:247], v[192:195], v[24:27]
	v_mfma_f32_16x16x32_bf16 v[0:3], v[248:251], v[192:195], v[0:3]
	v_mfma_f32_16x16x32_bf16 v[8:11], v[252:255], v[192:195], v[8:11]
	ds_read_b128 v[192:195], v134 offset:38912
	s_cmpk_eq_i32 s4, 0x700
	s_cbranch_scc1 .Lpk_150_3
	s_add_i32 m0, s101, 0xa000
	v_lshl_add_u64 v[136:137], v[136:137], 0, s[98:99]
	global_load_lds_dwordx4 v[136:137], off

.LBB0_165:
	s_and_b32 s27, s6, 0x10000
	s_xor_b32 s34, s27, 0x10000
	s_add_i32 s27, s27, 0
	s_add_i32 s101, s100, s34
	s_waitcnt lgkmcnt(3)
	v_mfma_f32_16x16x32_bf16 v[108:111], v[184:187], v[168:171], v[108:111]
	v_mfma_f32_16x16x32_bf16 v[92:95], v[184:187], v[172:175], v[92:95]
	v_mfma_f32_16x16x32_bf16 v[76:79], v[184:187], v[176:179], v[76:79]
	v_mfma_f32_16x16x32_bf16 v[60:63], v[184:187], v[180:183], v[60:63]
	ds_read_b128 v[240:243], v202
	ds_read_b128 v[244:247], v203
	s_cmpk_eq_i32 s30, 0
	s_cbranch_scc1 .Lpk_165_4
	s_add_i32 m0, s101, 0x4000
	v_lshl_add_u64 v[144:145], v[144:145], 0, s[98:99]
	global_load_lds_dwordx4 v[144:145], off
.Lpk_165_4:
	s_waitcnt lgkmcnt(4)
	v_mfma_f32_16x16x32_bf16 v[104:107], v[188:191], v[168:171], v[104:107]
	v_mfma_f32_16x16x32_bf16 v[88:91], v[188:191], v[172:175], v[88:91]
	v_mfma_f32_16x16x32_bf16 v[72:75], v[188:191], v[176:179], v[72:75]
	v_mfma_f32_16x16x32_bf16 v[56:59], v[188:191], v[180:183], v[56:59]
	ds_read_b128 v[248:251], v204
	ds_read_b128 v[252:255], v205
	s_cmpk_eq_i32 s30, 0
	s_cbranch_scc1 .Lpk_165_5
	s_add_i32 m0, s101, 0xc000
	v_lshl_add_u64 v[136:137], v[136:137], 0, s[98:99]
	global_load_lds_dwordx4 v[136:137], off
.Lpk_165_5:
	s_waitcnt lgkmcnt(5)
	v_mfma_f32_16x16x32_bf16 v[100:103], v[192:195], v[168:171], v[100:103]
	v_mfma_f32_16x16x32_bf16 v[84:87], v[192:195], v[172:175], v[84:87]
	v_mfma_f32_16x16x32_bf16 v[68:71], v[192:195], v[176:179], v[68:71]
	v_mfma_f32_16x16x32_bf16 v[52:55], v[192:195], v[180:183], v[52:55]
	s_cmpk_eq_i32 s30, 0
	s_cbranch_scc1 .Lpk_165_6
	s_add_i32 m0, s101, 0x6000
	v_lshl_add_u64 v[142:143], v[142:143], 0, s[98:99]
	global_load_lds_dwordx4 v[142:143], off
.Lpk_165_6:
	s_waitcnt lgkmcnt(4)
	v_mfma_f32_16x16x32_bf16 v[96:99], v[196:199], v[168:171], v[96:99]
	v_mfma_f32_16x16x32_bf16 v[80:83], v[196:199], v[172:175], v[80:83]
	v_mfma_f32_16x16x32_bf16 v[64:67], v[196:199], v[176:179], v[64:67]
	v_mfma_f32_16x16x32_bf16 v[48:51], v[196:199], v[180:183], v[48:51]
	s_cmpk_eq_i32 s30, 0
	s_cbranch_scc1 .Lpk_165_7
	s_add_i32 m0, s101, 0xe000
	v_lshl_add_u64 v[130:131], v[130:131], 0, s[98:99]
	global_load_lds_dwordx4 v[130:131], off
.Lpk_165_7:
	ds_read_b128 v[168:171], v162 offset:1024
	ds_read_b128 v[172:175], v163 offset:1024
	ds_read_b128 v[176:179], v200 offset:1024
	ds_read_b128 v[180:183], v201 offset:1024
	s_waitcnt lgkmcnt(4)
	v_mfma_f32_16x16x32_bf16 v[44:47], v[184:187], v[240:243], v[44:47]
	v_mfma_f32_16x16x32_bf16 v[28:31], v[184:187], v[244:247], v[28:31]
	v_mfma_f32_16x16x32_bf16 v[12:15], v[184:187], v[248:251], v[12:15]
	v_mfma_f32_16x16x32_bf16 v[112:115], v[184:187], v[252:255], v[112:115]
	ds_read_b128 v[184:187], v134 offset:33792
	v_mfma_f32_16x16x32_bf16 v[40:43], v[188:191], v[240:243], v[40:43]
	v_mfma_f32_16x16x32_bf16 v[24:27], v[188:191], v[244:247], v[24:27]
	v_mfma_f32_16x16x32_bf16 v[8:11], v[188:191], v[248:251], v[8:11]
	v_mfma_f32_16x16x32_bf16 v[116:119], v[188:191], v[252:255], v[116:119]
	ds_read_b128 v[188:191], v134 offset:35840
	v_mfma_f32_16x16x32_bf16 v[36:39], v[192:195], v[240:243], v[36:39]
	v_mfma_f32_16x16x32_bf16 v[20:23], v[192:195], v[244:247], v[20:23]
	v_mfma_f32_16x16x32_bf16 v[4:7], v[192:195], v[248:251], v[4:7]
	v_mfma_f32_16x16x32_bf16 v[120:123], v[192:195], v[252:255], v[120:123]
	ds_read_b128 v[192:195], v134 offset:37888
	v_mfma_f32_16x16x32_bf16 v[32:35], v[196:199], v[240:243], v[32:35]
	v_mfma_f32_16x16x32_bf16 v[16:19], v[196:199], v[244:247], v[16:19]
	v_mfma_f32_16x16x32_bf16 v[0:3], v[196:199], v[248:251], v[0:3]
	v_mfma_f32_16x16x32_bf16 v[124:127], v[196:199], v[252:255], v[124:127]
	ds_read_b128 v[196:199], v134 offset:39936
	s_waitcnt lgkmcnt(3)
	v_mfma_f32_16x16x32_bf16 v[108:111], v[184:187], v[168:171], v[108:111]
	v_mfma_f32_16x16x32_bf16 v[92:95], v[184:187], v[172:175], v[92:95]
	v_mfma_f32_16x16x32_bf16 v[76:79], v[184:187], v[176:179], v[76:79]
	v_mfma_f32_16x16x32_bf16 v[60:63], v[184:187], v[180:183], v[60:63]
	ds_read_b128 v[240:243], v202 offset:1024
	ds_read_b128 v[244:247], v203 offset:1024
	s_waitcnt lgkmcnt(4)
	v_mfma_f32_16x16x32_bf16 v[104:107], v[188:191], v[168:171], v[104:107]
	v_mfma_f32_16x16x32_bf16 v[88:91], v[188:191], v[172:175], v[88:91]
	v_mfma_f32_16x16x32_bf16 v[72:75], v[188:191], v[176:179], v[72:75]
	v_mfma_f32_16x16x32_bf16 v[56:59], v[188:191], v[180:183], v[56:59]
	ds_read_b128 v[248:251], v204 offset:1024
	ds_read_b128 v[252:255], v205 offset:1024
	s_waitcnt lgkmcnt(5)
	v_mfma_f32_16x16x32_bf16 v[100:103], v[192:195], v[168:171], v[100:103]
	v_mfma_f32_16x16x32_bf16 v[84:87], v[192:195], v[172:175], v[84:87]
	v_mfma_f32_16x16x32_bf16 v[68:71], v[192:195], v[176:179], v[68:71]
	v_mfma_f32_16x16x32_bf16 v[52:55], v[192:195], v[180:183], v[52:55]
	s_waitcnt lgkmcnt(4)
	v_mfma_f32_16x16x32_bf16 v[96:99], v[196:199], v[168:171], v[96:99]
	v_mfma_f32_16x16x32_bf16 v[80:83], v[196:199], v[172:175], v[80:83]
	v_mfma_f32_16x16x32_bf16 v[64:67], v[196:199], v[176:179], v[64:67]
	v_mfma_f32_16x16x32_bf16 v[48:51], v[196:199], v[180:183], v[48:51]
	s_waitcnt vmcnt(0) lgkmcnt(0)
	s_barrier
	s_add_i32 s101, s100, s27
	v_mfma_f32_16x16x32_bf16 v[44:47], v[184:187], v[240:243], v[44:47]
	v_mfma_f32_16x16x32_bf16 v[28:31], v[184:187], v[244:247], v[28:31]
	v_mfma_f32_16x16x32_bf16 v[12:15], v[184:187], v[248:251], v[12:15]
	v_mfma_f32_16x16x32_bf16 v[112:115], v[184:187], v[252:255], v[112:115]
	v_add3_u32 v134, s34, v151, v152
	ds_read_b128 v[184:187], v134 offset:32768
	v_add3_u32 v162, s34, v151, v153
	v_add3_u32 v163, s34, v155, v154
	v_add3_u32 v200, s34, v155, v156
	v_add3_u32 v201, s34, v155, v157
	ds_read_b128 v[168:171], v162
	ds_read_b128 v[172:175], v163
	ds_read_b128 v[176:179], v200
	ds_read_b128 v[180:183], v201
	s_cmpk_eq_i32 s30, 0x700
	s_cbranch_scc1 .Lpk_165_0
	s_mov_b32 m0, s101
	v_lshl_add_u64 v[148:149], v[148:149], 0, s[98:99]
	global_load_lds_dwordx4 v[148:149], off
.Lpk_165_0:
	v_mfma_f32_16x16x32_bf16 v[40:43], v[188:191], v[240:243], v[40:43]
	v_mfma_f32_16x16x32_bf16 v[24:27], v[188:191], v[244:247], v[24:27]
	v_mfma_f32_16x16x32_bf16 v[8:11], v[188:191], v[248:251], v[8:11]
	v_mfma_f32_16x16x32_bf16 v[116:119], v[188:191], v[252:255], v[116:119]
	ds_read_b128 v[188:191], v134 offset:34816
	v_add3_u32 v202, s34, v155, v158
	v_add3_u32 v203, s34, v155, v159
	v_add3_u32 v204, s34, v155, v160
	v_add3_u32 v205, s34, v155, v161
	s_cmpk_eq_i32 s30, 0x700
	s_cbranch_scc1 .Lpk_165_1
	s_add_i32 m0, s101, 0x8000
	v_lshl_add_u64 v[140:141], v[140:141], 0, s[98:99]
	global_load_lds_dwordx4 v[140:141], off
.Lpk_165_1:
	v_mfma_f32_16x16x32_bf16 v[36:39], v[192:195], v[240:243], v[36:39]
	v_mfma_f32_16x16x32_bf16 v[20:23], v[192:195], v[244:247], v[20:23]
	v_mfma_f32_16x16x32_bf16 v[4:7], v[192:195], v[248:251], v[4:7]
	v_mfma_f32_16x16x32_bf16 v[120:123], v[192:195], v[252:255], v[120:123]
	ds_read_b128 v[192:195], v134 offset:36864
	s_cmpk_eq_i32 s30, 0x700
	s_cbranch_scc1 .Lpk_165_2
	s_add_i32 m0, s101, 0x2000
	v_lshl_add_u64 v[146:147], v[146:147], 0, s[98:99]
	global_load_lds_dwordx4 v[146:147], off
.Lpk_165_2:
	v_mfma_f32_16x16x32_bf16 v[32:35], v[196:199], v[240:243], v[32:35]
	v_mfma_f32_16x16x32_bf16 v[16:19], v[196:199], v[244:247], v[16:19]
	v_mfma_f32_16x16x32_bf16 v[0:3], v[196:199], v[248:251], v[0:3]
	v_mfma_f32_16x16x32_bf16 v[124:127], v[196:199], v[252:255], v[124:127]
	ds_read_b128 v[196:199], v134 offset:38912
	s_cmpk_eq_i32 s30, 0x700
	s_cbranch_scc1 .Lpk_165_3
	s_add_i32 m0, s101, 0xa000
	v_lshl_add_u64 v[138:139], v[138:139], 0, s[98:99]
	global_load_lds_dwordx4 v[138:139], off

.LBB0_177:
	s_and_b32 s27, s6, 0x10000
	s_xor_b32 s30, s27, 0x10000
	s_add_i32 s27, s27, 0
	s_add_i32 s101, s100, s30
	s_waitcnt lgkmcnt(3)
	v_mfma_f32_16x16x32_bf16 v[108:111], v[160:163], v[180:183], v[108:111]
	v_mfma_f32_16x16x32_bf16 v[92:95], v[168:171], v[180:183], v[92:95]
	v_mfma_f32_16x16x32_bf16 v[76:79], v[172:175], v[180:183], v[76:79]
	v_mfma_f32_16x16x32_bf16 v[60:63], v[176:179], v[180:183], v[60:63]
	ds_read_b128 v[240:243], v200
	ds_read_b128 v[244:247], v201
	s_cmpk_eq_i32 s4, 0
	s_cbranch_scc1 .Lpk_177_4
	s_add_i32 m0, s101, 0x4000
	v_lshl_add_u64 v[142:143], v[142:143], 0, s[98:99]
	global_load_lds_dwordx4 v[142:143], off
.Lpk_177_4:
	s_waitcnt lgkmcnt(4)
	v_mfma_f32_16x16x32_bf16 v[104:107], v[160:163], v[184:187], v[104:107]
	v_mfma_f32_16x16x32_bf16 v[88:91], v[168:171], v[184:187], v[88:91]
	v_mfma_f32_16x16x32_bf16 v[72:75], v[172:175], v[184:187], v[72:75]
	v_mfma_f32_16x16x32_bf16 v[56:59], v[176:179], v[184:187], v[56:59]
	ds_read_b128 v[248:251], v202
	ds_read_b128 v[252:255], v203
	s_cmpk_eq_i32 s4, 0
	s_cbranch_scc1 .Lpk_177_5
	s_add_i32 m0, s101, 0xc000
	v_lshl_add_u64 v[130:131], v[130:131], 0, s[98:99]
	global_load_lds_dwordx4 v[130:131], off
.Lpk_177_5:
	s_waitcnt lgkmcnt(5)
	v_mfma_f32_16x16x32_bf16 v[100:103], v[160:163], v[188:191], v[100:103]
	v_mfma_f32_16x16x32_bf16 v[84:87], v[168:171], v[188:191], v[84:87]
	v_mfma_f32_16x16x32_bf16 v[68:71], v[172:175], v[188:191], v[68:71]
	v_mfma_f32_16x16x32_bf16 v[52:55], v[176:179], v[188:191], v[52:55]
	s_cmpk_eq_i32 s4, 0
	s_cbranch_scc1 .Lpk_177_6
	s_add_i32 m0, s101, 0x6000
	v_lshl_add_u64 v[140:141], v[140:141], 0, s[98:99]
	global_load_lds_dwordx4 v[140:141], off
.Lpk_177_6:
	s_waitcnt lgkmcnt(4)
	v_mfma_f32_16x16x32_bf16 v[96:99], v[160:163], v[192:195], v[96:99]
	v_mfma_f32_16x16x32_bf16 v[80:83], v[168:171], v[192:195], v[80:83]
	v_mfma_f32_16x16x32_bf16 v[64:67], v[172:175], v[192:195], v[64:67]
	v_mfma_f32_16x16x32_bf16 v[48:51], v[176:179], v[192:195], v[48:51]
	s_cmpk_eq_i32 s4, 0
	s_cbranch_scc1 .Lpk_177_7
	s_add_i32 m0, s101, 0xe000
	v_lshl_add_u64 v[128:129], v[128:129], 0, s[98:99]
	global_load_lds_dwordx4 v[128:129], off
.Lpk_177_7:
	ds_read_b128 v[160:163], v196 offset:1024
	ds_read_b128 v[168:171], v197 offset:1024
	ds_read_b128 v[172:175], v198 offset:1024
	ds_read_b128 v[176:179], v199 offset:1024
	s_waitcnt lgkmcnt(4)
	v_mfma_f32_16x16x32_bf16 v[44:47], v[240:243], v[180:183], v[44:47]
	v_mfma_f32_16x16x32_bf16 v[28:31], v[244:247], v[180:183], v[28:31]
	v_mfma_f32_16x16x32_bf16 v[12:15], v[248:251], v[180:183], v[12:15]
	v_mfma_f32_16x16x32_bf16 v[112:115], v[252:255], v[180:183], v[112:115]
	ds_read_b128 v[180:183], v134 offset:33792
	v_mfma_f32_16x16x32_bf16 v[40:43], v[240:243], v[184:187], v[40:43]
	v_mfma_f32_16x16x32_bf16 v[24:27], v[244:247], v[184:187], v[24:27]
	v_mfma_f32_16x16x32_bf16 v[8:11], v[248:251], v[184:187], v[8:11]
	v_mfma_f32_16x16x32_bf16 v[116:119], v[252:255], v[184:187], v[116:119]
	ds_read_b128 v[184:187], v134 offset:35840
	v_mfma_f32_16x16x32_bf16 v[36:39], v[240:243], v[188:191], v[36:39]
	v_mfma_f32_16x16x32_bf16 v[20:23], v[244:247], v[188:191], v[20:23]
	v_mfma_f32_16x16x32_bf16 v[4:7], v[248:251], v[188:191], v[4:7]
	v_mfma_f32_16x16x32_bf16 v[120:123], v[252:255], v[188:191], v[120:123]
	ds_read_b128 v[188:191], v134 offset:37888
	v_mfma_f32_16x16x32_bf16 v[32:35], v[240:243], v[192:195], v[32:35]
	v_mfma_f32_16x16x32_bf16 v[16:19], v[244:247], v[192:195], v[16:19]
	v_mfma_f32_16x16x32_bf16 v[0:3], v[248:251], v[192:195], v[0:3]
	v_mfma_f32_16x16x32_bf16 v[124:127], v[252:255], v[192:195], v[124:127]
	ds_read_b128 v[192:195], v134 offset:39936
	s_waitcnt lgkmcnt(3)
	v_mfma_f32_16x16x32_bf16 v[108:111], v[160:163], v[180:183], v[108:111]
	v_mfma_f32_16x16x32_bf16 v[92:95], v[168:171], v[180:183], v[92:95]
	v_mfma_f32_16x16x32_bf16 v[76:79], v[172:175], v[180:183], v[76:79]
	v_mfma_f32_16x16x32_bf16 v[60:63], v[176:179], v[180:183], v[60:63]
	ds_read_b128 v[240:243], v200 offset:1024
	ds_read_b128 v[244:247], v201 offset:1024
	s_waitcnt lgkmcnt(4)
	v_mfma_f32_16x16x32_bf16 v[104:107], v[160:163], v[184:187], v[104:107]
	v_mfma_f32_16x16x32_bf16 v[88:91], v[168:171], v[184:187], v[88:91]
	v_mfma_f32_16x16x32_bf16 v[72:75], v[172:175], v[184:187], v[72:75]
	v_mfma_f32_16x16x32_bf16 v[56:59], v[176:179], v[184:187], v[56:59]
	ds_read_b128 v[248:251], v202 offset:1024
	ds_read_b128 v[252:255], v203 offset:1024
	s_waitcnt lgkmcnt(5)
	v_mfma_f32_16x16x32_bf16 v[100:103], v[160:163], v[188:191], v[100:103]
	v_mfma_f32_16x16x32_bf16 v[84:87], v[168:171], v[188:191], v[84:87]
	v_mfma_f32_16x16x32_bf16 v[68:71], v[172:175], v[188:191], v[68:71]
	v_mfma_f32_16x16x32_bf16 v[52:55], v[176:179], v[188:191], v[52:55]
	s_waitcnt lgkmcnt(4)
	v_mfma_f32_16x16x32_bf16 v[96:99], v[160:163], v[192:195], v[96:99]
	v_mfma_f32_16x16x32_bf16 v[80:83], v[168:171], v[192:195], v[80:83]
	v_mfma_f32_16x16x32_bf16 v[64:67], v[172:175], v[192:195], v[64:67]
	v_mfma_f32_16x16x32_bf16 v[48:51], v[176:179], v[192:195], v[48:51]
	s_waitcnt vmcnt(0) lgkmcnt(0)
	s_barrier
	s_add_i32 s101, s100, s27
	v_mfma_f32_16x16x32_bf16 v[44:47], v[240:243], v[180:183], v[44:47]
	v_mfma_f32_16x16x32_bf16 v[28:31], v[244:247], v[180:183], v[28:31]
	v_mfma_f32_16x16x32_bf16 v[12:15], v[248:251], v[180:183], v[12:15]
	v_mfma_f32_16x16x32_bf16 v[112:115], v[252:255], v[180:183], v[112:115]
	v_add3_u32 v134, s30, v149, v150
	ds_read_b128 v[180:183], v134 offset:32768
	v_add3_u32 v196, s30, v149, v151
	v_add3_u32 v197, s30, v153, v152
	v_add3_u32 v198, s30, v153, v154
	v_add3_u32 v199, s30, v153, v155
	ds_read_b128 v[160:163], v196
	ds_read_b128 v[168:171], v197
	ds_read_b128 v[172:175], v198
	ds_read_b128 v[176:179], v199
	s_cmpk_eq_i32 s4, 0x700
	s_cbranch_scc1 .Lpk_177_0
	s_mov_b32 m0, s101
	v_lshl_add_u64 v[146:147], v[146:147], 0, s[98:99]
	global_load_lds_dwordx4 v[146:147], off
.Lpk_177_0:
	v_mfma_f32_16x16x32_bf16 v[40:43], v[240:243], v[184:187], v[40:43]
	v_mfma_f32_16x16x32_bf16 v[24:27], v[244:247], v[184:187], v[24:27]
	v_mfma_f32_16x16x32_bf16 v[8:11], v[248:251], v[184:187], v[8:11]
	v_mfma_f32_16x16x32_bf16 v[116:119], v[252:255], v[184:187], v[116:119]
	ds_read_b128 v[184:187], v134 offset:34816
	v_add3_u32 v200, s30, v153, v156
	v_add3_u32 v201, s30, v153, v157
	v_add3_u32 v202, s30, v153, v158
	v_add3_u32 v203, s30, v153, v159
	s_cmpk_eq_i32 s4, 0x700
	s_cbranch_scc1 .Lpk_177_1
	s_add_i32 m0, s101, 0x8000
	v_lshl_add_u64 v[138:139], v[138:139], 0, s[98:99]
	global_load_lds_dwordx4 v[138:139], off
.Lpk_177_1:
	v_mfma_f32_16x16x32_bf16 v[36:39], v[240:243], v[188:191], v[36:39]
	v_mfma_f32_16x16x32_bf16 v[20:23], v[244:247], v[188:191], v[20:23]
	v_mfma_f32_16x16x32_bf16 v[4:7], v[248:251], v[188:191], v[4:7]
	v_mfma_f32_16x16x32_bf16 v[120:123], v[252:255], v[188:191], v[120:123]
	ds_read_b128 v[188:191], v134 offset:36864
	s_cmpk_eq_i32 s4, 0x700
	s_cbranch_scc1 .Lpk_177_2
	s_add_i32 m0, s101, 0x2000
	v_lshl_add_u64 v[144:145], v[144:145], 0, s[98:99]
	global_load_lds_dwordx4 v[144:145], off
.Lpk_177_2:
	v_mfma_f32_16x16x32_bf16 v[32:35], v[240:243], v[192:195], v[32:35]
	v_mfma_f32_16x16x32_bf16 v[16:19], v[244:247], v[192:195], v[16:19]
	v_mfma_f32_16x16x32_bf16 v[0:3], v[248:251], v[192:195], v[0:3]
	v_mfma_f32_16x16x32_bf16 v[124:127], v[252:255], v[192:195], v[124:127]
	ds_read_b128 v[192:195], v134 offset:38912
	s_cmpk_eq_i32 s4, 0x700
	s_cbranch_scc1 .Lpk_177_3
	s_add_i32 m0, s101, 0xa000
	v_lshl_add_u64 v[136:137], v[136:137], 0, s[98:99]
	global_load_lds_dwordx4 v[136:137], off

.LBB0_181:
	s_and_b32 s27, s6, 0x10000
	s_xor_b32 s28, s27, 0x10000
	s_add_i32 s27, s27, 0
	s_add_i32 s101, s100, s28
	s_waitcnt lgkmcnt(3)
	v_mfma_f32_16x16x32_bf16 v[124:127], v[184:187], v[168:171], v[124:127]
	v_mfma_f32_16x16x32_bf16 v[108:111], v[184:187], v[172:175], v[108:111]
	v_mfma_f32_16x16x32_bf16 v[92:95], v[184:187], v[176:179], v[92:95]
	v_mfma_f32_16x16x32_bf16 v[76:79], v[184:187], v[180:183], v[76:79]
	ds_read_b128 v[240:243], v202
	ds_read_b128 v[244:247], v203
	s_cmpk_eq_i32 s4, 0
	s_cbranch_scc1 .Lpk_181_4
	s_add_i32 m0, s101, 0x4000
	v_lshl_add_u64 v[144:145], v[144:145], 0, s[98:99]
	global_load_lds_dwordx4 v[144:145], off
.Lpk_181_4:
	s_waitcnt lgkmcnt(4)
	v_mfma_f32_16x16x32_bf16 v[120:123], v[188:191], v[168:171], v[120:123]
	v_mfma_f32_16x16x32_bf16 v[104:107], v[188:191], v[172:175], v[104:107]
	v_mfma_f32_16x16x32_bf16 v[88:91], v[188:191], v[176:179], v[88:91]
	v_mfma_f32_16x16x32_bf16 v[72:75], v[188:191], v[180:183], v[72:75]
	ds_read_b128 v[248:251], v204
	ds_read_b128 v[252:255], v205
	s_cmpk_eq_i32 s4, 0
	s_cbranch_scc1 .Lpk_181_5
	s_add_i32 m0, s101, 0xc000
	v_lshl_add_u64 v[136:137], v[136:137], 0, s[98:99]
	global_load_lds_dwordx4 v[136:137], off
.Lpk_181_5:
	s_waitcnt lgkmcnt(5)
	v_mfma_f32_16x16x32_bf16 v[116:119], v[192:195], v[168:171], v[116:119]
	v_mfma_f32_16x16x32_bf16 v[100:103], v[192:195], v[172:175], v[100:103]
	v_mfma_f32_16x16x32_bf16 v[84:87], v[192:195], v[176:179], v[84:87]
	v_mfma_f32_16x16x32_bf16 v[68:71], v[192:195], v[180:183], v[68:71]
	s_cmpk_eq_i32 s4, 0
	s_cbranch_scc1 .Lpk_181_6
	s_add_i32 m0, s101, 0x6000
	v_lshl_add_u64 v[142:143], v[142:143], 0, s[98:99]
	global_load_lds_dwordx4 v[142:143], off
.Lpk_181_6:
	s_waitcnt lgkmcnt(4)
	v_mfma_f32_16x16x32_bf16 v[112:115], v[196:199], v[168:171], v[112:115]
	v_mfma_f32_16x16x32_bf16 v[96:99], v[196:199], v[172:175], v[96:99]
	v_mfma_f32_16x16x32_bf16 v[80:83], v[196:199], v[176:179], v[80:83]
	v_mfma_f32_16x16x32_bf16 v[64:67], v[196:199], v[180:183], v[64:67]
	s_cmpk_eq_i32 s4, 0
	s_cbranch_scc1 .Lpk_181_7
	s_add_i32 m0, s101, 0xe000
	v_lshl_add_u64 v[130:131], v[130:131], 0, s[98:99]
	global_load_lds_dwordx4 v[130:131], off
.Lpk_181_7:
	ds_read_b128 v[168:171], v162 offset:1024
	ds_read_b128 v[172:175], v163 offset:1024
	ds_read_b128 v[176:179], v200 offset:1024
	ds_read_b128 v[180:183], v201 offset:1024
	s_waitcnt lgkmcnt(4)
	v_mfma_f32_16x16x32_bf16 v[60:63], v[184:187], v[240:243], v[60:63]
	v_mfma_f32_16x16x32_bf16 v[44:47], v[184:187], v[244:247], v[44:47]
	v_mfma_f32_16x16x32_bf16 v[16:19], v[184:187], v[248:251], v[16:19]
	v_mfma_f32_16x16x32_bf16 v[36:39], v[184:187], v[252:255], v[36:39]
	ds_read_b128 v[184:187], v161 offset:33792
	v_mfma_f32_16x16x32_bf16 v[56:59], v[188:191], v[240:243], v[56:59]
	v_mfma_f32_16x16x32_bf16 v[40:43], v[188:191], v[244:247], v[40:43]
	v_mfma_f32_16x16x32_bf16 v[12:15], v[188:191], v[248:251], v[12:15]
	v_mfma_f32_16x16x32_bf16 v[28:31], v[188:191], v[252:255], v[28:31]
	ds_read_b128 v[188:191], v161 offset:35840
	v_mfma_f32_16x16x32_bf16 v[52:55], v[192:195], v[240:243], v[52:55]
	v_mfma_f32_16x16x32_bf16 v[32:35], v[192:195], v[244:247], v[32:35]
	v_mfma_f32_16x16x32_bf16 v[4:7], v[192:195], v[248:251], v[4:7]
	v_mfma_f32_16x16x32_bf16 v[20:23], v[192:195], v[252:255], v[20:23]
	ds_read_b128 v[192:195], v161 offset:37888
	v_mfma_f32_16x16x32_bf16 v[48:51], v[196:199], v[240:243], v[48:51]
	v_mfma_f32_16x16x32_bf16 v[24:27], v[196:199], v[244:247], v[24:27]
	v_mfma_f32_16x16x32_bf16 v[0:3], v[196:199], v[248:251], v[0:3]
	v_mfma_f32_16x16x32_bf16 v[8:11], v[196:199], v[252:255], v[8:11]
	ds_read_b128 v[196:199], v161 offset:39936
	s_waitcnt lgkmcnt(3)
	v_mfma_f32_16x16x32_bf16 v[124:127], v[184:187], v[168:171], v[124:127]
	v_mfma_f32_16x16x32_bf16 v[108:111], v[184:187], v[172:175], v[108:111]
	v_mfma_f32_16x16x32_bf16 v[92:95], v[184:187], v[176:179], v[92:95]
	v_mfma_f32_16x16x32_bf16 v[76:79], v[184:187], v[180:183], v[76:79]
	ds_read_b128 v[240:243], v202 offset:1024
	ds_read_b128 v[244:247], v203 offset:1024
	s_waitcnt lgkmcnt(4)
	v_mfma_f32_16x16x32_bf16 v[120:123], v[188:191], v[168:171], v[120:123]
	v_mfma_f32_16x16x32_bf16 v[104:107], v[188:191], v[172:175], v[104:107]
	v_mfma_f32_16x16x32_bf16 v[88:91], v[188:191], v[176:179], v[88:91]
	v_mfma_f32_16x16x32_bf16 v[72:75], v[188:191], v[180:183], v[72:75]
	ds_read_b128 v[248:251], v204 offset:1024
	ds_read_b128 v[252:255], v205 offset:1024
	s_waitcnt lgkmcnt(5)
	v_mfma_f32_16x16x32_bf16 v[116:119], v[192:195], v[168:171], v[116:119]
	v_mfma_f32_16x16x32_bf16 v[100:103], v[192:195], v[172:175], v[100:103]
	v_mfma_f32_16x16x32_bf16 v[84:87], v[192:195], v[176:179], v[84:87]
	v_mfma_f32_16x16x32_bf16 v[68:71], v[192:195], v[180:183], v[68:71]
	s_waitcnt lgkmcnt(4)
	v_mfma_f32_16x16x32_bf16 v[112:115], v[196:199], v[168:171], v[112:115]
	v_mfma_f32_16x16x32_bf16 v[96:99], v[196:199], v[172:175], v[96:99]
	v_mfma_f32_16x16x32_bf16 v[80:83], v[196:199], v[176:179], v[80:83]
	v_mfma_f32_16x16x32_bf16 v[64:67], v[196:199], v[180:183], v[64:67]
	s_waitcnt vmcnt(0) lgkmcnt(0)
	s_barrier
	s_add_i32 s101, s100, s27
	v_mfma_f32_16x16x32_bf16 v[60:63], v[184:187], v[240:243], v[60:63]
	v_mfma_f32_16x16x32_bf16 v[44:47], v[184:187], v[244:247], v[44:47]
	v_mfma_f32_16x16x32_bf16 v[16:19], v[184:187], v[248:251], v[16:19]
	v_mfma_f32_16x16x32_bf16 v[36:39], v[184:187], v[252:255], v[36:39]
	v_add3_u32 v161, s28, v151, v152
	ds_read_b128 v[184:187], v161 offset:32768
	v_add3_u32 v162, s28, v151, v153
	v_add3_u32 v163, s28, v154, v134
	v_add3_u32 v200, s28, v154, v155
	v_add3_u32 v201, s28, v154, v156
	ds_read_b128 v[168:171], v162
	ds_read_b128 v[172:175], v163
	ds_read_b128 v[176:179], v200
	ds_read_b128 v[180:183], v201
	s_cmpk_eq_i32 s4, 0x700
	s_cbranch_scc1 .Lpk_181_0
	s_mov_b32 m0, s101
	v_lshl_add_u64 v[148:149], v[148:149], 0, s[98:99]
	global_load_lds_dwordx4 v[148:149], off
.Lpk_181_0:
	v_mfma_f32_16x16x32_bf16 v[56:59], v[188:191], v[240:243], v[56:59]
	v_mfma_f32_16x16x32_bf16 v[40:43], v[188:191], v[244:247], v[40:43]
	v_mfma_f32_16x16x32_bf16 v[12:15], v[188:191], v[248:251], v[12:15]
	v_mfma_f32_16x16x32_bf16 v[28:31], v[188:191], v[252:255], v[28:31]
	ds_read_b128 v[188:191], v161 offset:34816
	v_add3_u32 v202, s28, v154, v157
	v_add3_u32 v203, s28, v154, v158
	v_add3_u32 v204, s28, v154, v159
	v_add3_u32 v205, s28, v154, v160
	s_cmpk_eq_i32 s4, 0x700
	s_cbranch_scc1 .Lpk_181_1
	s_add_i32 m0, s101, 0x8000
	v_lshl_add_u64 v[140:141], v[140:141], 0, s[98:99]
	global_load_lds_dwordx4 v[140:141], off
.Lpk_181_1:
	v_mfma_f32_16x16x32_bf16 v[52:55], v[192:195], v[240:243], v[52:55]
	v_mfma_f32_16x16x32_bf16 v[32:35], v[192:195], v[244:247], v[32:35]
	v_mfma_f32_16x16x32_bf16 v[4:7], v[192:195], v[248:251], v[4:7]
	v_mfma_f32_16x16x32_bf16 v[20:23], v[192:195], v[252:255], v[20:23]
	ds_read_b128 v[192:195], v161 offset:36864
	s_cmpk_eq_i32 s4, 0x700
	s_cbranch_scc1 .Lpk_181_2
	s_add_i32 m0, s101, 0x2000
	v_lshl_add_u64 v[146:147], v[146:147], 0, s[98:99]
	global_load_lds_dwordx4 v[146:147], off
.Lpk_181_2:
	v_mfma_f32_16x16x32_bf16 v[48:51], v[196:199], v[240:243], v[48:51]
	v_mfma_f32_16x16x32_bf16 v[24:27], v[196:199], v[244:247], v[24:27]
	v_mfma_f32_16x16x32_bf16 v[0:3], v[196:199], v[248:251], v[0:3]
	v_mfma_f32_16x16x32_bf16 v[8:11], v[196:199], v[252:255], v[8:11]
	ds_read_b128 v[196:199], v161 offset:38912
	s_cmpk_eq_i32 s4, 0x700
	s_cbranch_scc1 .Lpk_181_3
	s_add_i32 m0, s101, 0xa000
	v_lshl_add_u64 v[138:139], v[138:139], 0, s[98:99]
	global_load_lds_dwordx4 v[138:139], off

.LBB0_511:
	s_or_b64 exec, exec, s[20:21]
	v_ashrrev_i32_e32 v94, 7, v71
	v_and_b32_e32 v114, 31, v71
	v_ashrrev_i32_e32 v95, 31, v94
	v_lshlrev_b64 v[118:119], 12, v[94:95]
	v_lshlrev_b32_e32 v112, 7, v114
	v_lshlrev_b32_e32 v68, 8, v116
	v_or_b32_e32 v26, v118, v112
	v_mov_b32_e32 v93, v69
	s_waitcnt vmcnt(0)
	v_lshl_add_u64 v[4:5], v[2:3], 0, v[68:69]
	v_lshl_add_u64 v[8:9], v[4:5], 0, v[92:93]
	s_mov_b64 s[20:21], 0xc800000
	v_or_b32_e32 v118, v26, v70
	v_lshl_add_u64 v[10:11], v[8:9], 0, s[20:21]
	v_lshlrev_b64 v[12:13], 10, v[118:119]
	v_lshl_add_u64 v[96:97], v[10:11], 0, v[12:13]
	v_or_b32_e32 v120, v26, v72
	v_mov_b32_e32 v121, v119
	v_lshlrev_b64 v[14:15], 10, v[120:121]
	v_lshl_add_u64 v[98:99], v[10:11], 0, v[14:15]
	v_or_b32_e32 v122, v26, v74
	v_mov_b32_e32 v123, v119
	v_lshlrev_b64 v[16:17], 10, v[122:123]
	v_lshl_add_u64 v[100:101], v[10:11], 0, v[16:17]
	v_or_b32_e32 v124, v26, v76
	v_mov_b32_e32 v125, v119
	v_lshlrev_b64 v[18:19], 10, v[124:125]
	v_lshl_add_u64 v[102:103], v[10:11], 0, v[18:19]
	v_or_b32_e32 v126, v26, v78
	v_mov_b32_e32 v127, v119
	v_lshlrev_b64 v[20:21], 10, v[126:127]
	v_lshl_add_u64 v[104:105], v[10:11], 0, v[20:21]
	v_or_b32_e32 v128, v26, v80
	v_mov_b32_e32 v129, v119
	v_lshlrev_b64 v[22:23], 10, v[128:129]
	v_lshl_add_u64 v[106:107], v[10:11], 0, v[22:23]
	v_or_b32_e32 v130, v26, v82
	v_mov_b32_e32 v131, v119
	v_lshlrev_b64 v[24:25], 10, v[130:131]
	v_lshl_add_u64 v[108:109], v[10:11], 0, v[24:25]
	v_or_b32_e32 v134, v26, v84
	v_mov_b32_e32 v135, v119
	v_lshlrev_b64 v[26:27], 10, v[134:135]
	v_lshl_add_u64 v[110:111], v[10:11], 0, v[26:27]
	s_mov_b64 s[20:21], 0xe800000
	v_lshl_add_u64 v[8:9], v[8:9], 0, s[20:21]
	v_lshrrev_b32_e32 v215, 5, v71
	s_mov_b32 s20, 0
	v_lshl_add_u64 v[240:241], v[8:9], 0, v[12:13]
	v_lshl_add_u64 v[242:243], v[8:9], 0, v[14:15]
	v_lshl_add_u64 v[244:245], v[8:9], 0, v[16:17]
	v_lshl_add_u64 v[246:247], v[8:9], 0, v[18:19]
	v_lshl_add_u64 v[248:249], v[8:9], 0, v[20:21]
	v_lshl_add_u64 v[250:251], v[8:9], 0, v[22:23]
	v_lshl_add_u64 v[252:253], v[8:9], 0, v[24:25]
	v_lshl_add_u64 v[254:255], v[8:9], 0, v[26:27]
	global_load_dwordx4 v[4:7], v[96:97], off
	global_load_dwordx4 v[8:11], v[98:99], off
	global_load_dwordx4 v[12:15], v[100:101], off
	global_load_dwordx4 v[16:19], v[102:103], off
	global_load_dwordx4 v[20:23], v[104:105], off
	global_load_dwordx4 v[24:27], v[106:107], off
	global_load_dwordx4 v[28:31], v[108:109], off
	global_load_dwordx4 v[32:35], v[110:111], off
	global_load_dwordx4 v[36:39], v[240:241], off
	global_load_dwordx4 v[40:43], v[242:243], off
	global_load_dwordx4 v[44:47], v[244:245], off
	global_load_dwordx4 v[48:51], v[246:247], off
	global_load_dwordx4 v[52:55], v[248:249], off
	global_load_dwordx4 v[56:59], v[250:251], off
	global_load_dwordx4 v[60:63], v[252:253], off
	global_load_dwordx4 v[64:67], v[254:255], off
	s_waitcnt vmcnt(0) lgkmcnt(0)
	ds_write_b128 v85, v[4:7]
	ds_write_b128 v85, v[8:11] offset:4352
	ds_write_b128 v85, v[12:15] offset:8704
	ds_write_b128 v85, v[16:19] offset:13056
	ds_write_b128 v85, v[20:23] offset:17408
	ds_write_b128 v85, v[24:27] offset:21760
	ds_write_b128 v133, v[28:31] offset:4352
	ds_write_b128 v133, v[32:35] offset:8704
	ds_write_b128 v85, v[36:39] offset:34816
	ds_write_b128 v85, v[40:43] offset:39168
	ds_write_b128 v85, v[44:47] offset:43520
	ds_write_b128 v85, v[48:51] offset:47872
	ds_write_b128 v85, v[52:55] offset:52224
	ds_write_b128 v133, v[56:59] offset:34816
	ds_write_b128 v133, v[60:63] offset:39168
	ds_write_b128 v133, v[64:67] offset:43520
	v_mov_b32_e32 v64, 0
	v_mov_b32_e32 v65, v64
	v_mov_b32_e32 v66, v64
	v_mov_b32_e32 v67, v64
	v_mov_b32_e32 v60, v64
	v_mov_b32_e32 v61, v64
	v_mov_b32_e32 v62, v64
	v_mov_b32_e32 v63, v64
	v_mov_b32_e32 v56, v64
	v_mov_b32_e32 v57, v64
	v_mov_b32_e32 v58, v64
	v_mov_b32_e32 v59, v64
	v_mov_b32_e32 v52, v64
	v_mov_b32_e32 v53, v64
	v_mov_b32_e32 v54, v64
	v_mov_b32_e32 v55, v64
	v_mov_b32_e32 v48, v64
	v_mov_b32_e32 v49, v64
	v_mov_b32_e32 v50, v64
	v_mov_b32_e32 v51, v64
	v_mov_b32_e32 v44, v64
	v_mov_b32_e32 v45, v64
	v_mov_b32_e32 v46, v64
	v_mov_b32_e32 v47, v64
	v_mov_b32_e32 v40, v64
	v_mov_b32_e32 v41, v64
	v_mov_b32_e32 v42, v64
	v_mov_b32_e32 v43, v64
	v_mov_b32_e32 v36, v64
	v_mov_b32_e32 v37, v64
	v_mov_b32_e32 v38, v64
	v_mov_b32_e32 v39, v64
	v_mov_b32_e32 v32, v64
	v_mov_b32_e32 v33, v64
	v_mov_b32_e32 v34, v64
	v_mov_b32_e32 v35, v64
	v_mov_b32_e32 v28, v64
	v_mov_b32_e32 v29, v64
	v_mov_b32_e32 v30, v64
	v_mov_b32_e32 v31, v64
	v_mov_b32_e32 v10, v64
	v_mov_b32_e32 v11, v64
	v_mov_b32_e32 v12, v64
	v_mov_b32_e32 v13, v64
	v_mov_b32_e32 v14, v64
	v_mov_b32_e32 v15, v64
	v_mov_b32_e32 v16, v64
	v_mov_b32_e32 v17, v64
	v_mov_b32_e32 v18, v64
	v_mov_b32_e32 v19, v64
	v_mov_b32_e32 v20, v64
	v_mov_b32_e32 v21, v64
	v_mov_b32_e32 v22, v64
	v_mov_b32_e32 v23, v64
	v_mov_b32_e32 v24, v64
	v_mov_b32_e32 v25, v64
	v_mov_b32_e32 v26, v64
	v_mov_b32_e32 v27, v64
	v_mov_b32_e32 v8, v64
	v_mov_b32_e32 v9, v64
	v_mov_b32_e32 v4, v64
	v_mov_b32_e32 v5, v64
	v_mov_b32_e32 v6, v64
	v_mov_b32_e32 v7, v64
	s_waitcnt lgkmcnt(0)
	s_barrier

.LBB0_793:
	s_and_b32 s31, s0, 0x10000
	s_xor_b32 s42, s31, 0x10000
	s_add_i32 s31, s31, 0
	s_add_i32 s101, s100, s42
	s_waitcnt lgkmcnt(3)
	v_mfma_f32_16x16x32_bf16 v[126:129], v[180:183], v[164:167], v[126:129]
	v_mfma_f32_16x16x32_bf16 v[110:113], v[180:183], v[168:171], v[110:113]
	v_mfma_f32_16x16x32_bf16 v[94:97], v[180:183], v[172:175], v[94:97]
	v_mfma_f32_16x16x32_bf16 v[78:81], v[180:183], v[176:179], v[78:81]
	ds_read_b128 v[240:243], v199
	ds_read_b128 v[244:247], v200
	s_cmpk_eq_i32 s38, 0
	s_cbranch_scc1 .Lpk_793_4
	s_add_i32 m0, s101, 0x4000
	v_lshl_add_u64 v[144:145], v[144:145], 0, s[98:99]
	global_load_lds_dwordx4 v[144:145], off
.Lpk_793_4:
	s_waitcnt lgkmcnt(4)
	v_mfma_f32_16x16x32_bf16 v[122:125], v[184:187], v[164:167], v[122:125]
	v_mfma_f32_16x16x32_bf16 v[106:109], v[184:187], v[168:171], v[106:109]
	v_mfma_f32_16x16x32_bf16 v[90:93], v[184:187], v[172:175], v[90:93]
	v_mfma_f32_16x16x32_bf16 v[74:77], v[184:187], v[176:179], v[74:77]
	ds_read_b128 v[248:251], v201
	ds_read_b128 v[252:255], v202
	s_cmpk_eq_i32 s38, 0
	s_cbranch_scc1 .Lpk_793_5
	s_add_i32 m0, s101, 0xc000
	v_lshl_add_u64 v[136:137], v[136:137], 0, s[98:99]
	global_load_lds_dwordx4 v[136:137], off
.Lpk_793_5:
	s_waitcnt lgkmcnt(5)
	v_mfma_f32_16x16x32_bf16 v[118:121], v[188:191], v[164:167], v[118:121]
	v_mfma_f32_16x16x32_bf16 v[102:105], v[188:191], v[168:171], v[102:105]
	v_mfma_f32_16x16x32_bf16 v[86:89], v[188:191], v[172:175], v[86:89]
	v_mfma_f32_16x16x32_bf16 v[70:73], v[188:191], v[176:179], v[70:73]
	s_cmpk_eq_i32 s38, 0
	s_cbranch_scc1 .Lpk_793_6
	s_add_i32 m0, s101, 0x6000
	v_lshl_add_u64 v[142:143], v[142:143], 0, s[98:99]
	global_load_lds_dwordx4 v[142:143], off
.Lpk_793_6:
	s_waitcnt lgkmcnt(4)
	v_mfma_f32_16x16x32_bf16 v[114:117], v[192:195], v[164:167], v[114:117]
	v_mfma_f32_16x16x32_bf16 v[98:101], v[192:195], v[168:171], v[98:101]
	v_mfma_f32_16x16x32_bf16 v[82:85], v[192:195], v[172:175], v[82:85]
	v_mfma_f32_16x16x32_bf16 v[66:69], v[192:195], v[176:179], v[66:69]
	s_cmpk_eq_i32 s38, 0
	s_cbranch_scc1 .Lpk_793_7
	s_add_i32 m0, s101, 0xe000
	v_lshl_add_u64 v[134:135], v[134:135], 0, s[98:99]
	global_load_lds_dwordx4 v[134:135], off
.Lpk_793_7:
	ds_read_b128 v[164:167], v163 offset:1024
	ds_read_b128 v[168:171], v196 offset:1024
	ds_read_b128 v[172:175], v197 offset:1024
	ds_read_b128 v[176:179], v198 offset:1024
	s_waitcnt lgkmcnt(4)
	v_mfma_f32_16x16x32_bf16 v[62:65], v[180:183], v[240:243], v[62:65]
	v_mfma_f32_16x16x32_bf16 v[46:49], v[180:183], v[244:247], v[46:49]
	v_mfma_f32_16x16x32_bf16 v[18:21], v[180:183], v[248:251], v[18:21]
	v_mfma_f32_16x16x32_bf16 v[38:41], v[180:183], v[252:255], v[38:41]
	ds_read_b128 v[180:183], v130 offset:33792
	v_mfma_f32_16x16x32_bf16 v[58:61], v[184:187], v[240:243], v[58:61]
	v_mfma_f32_16x16x32_bf16 v[42:45], v[184:187], v[244:247], v[42:45]
	v_mfma_f32_16x16x32_bf16 v[10:13], v[184:187], v[248:251], v[10:13]
	v_mfma_f32_16x16x32_bf16 v[30:33], v[184:187], v[252:255], v[30:33]
	ds_read_b128 v[184:187], v130 offset:35840
	v_mfma_f32_16x16x32_bf16 v[54:57], v[188:191], v[240:243], v[54:57]
	v_mfma_f32_16x16x32_bf16 v[34:37], v[188:191], v[244:247], v[34:37]
	v_mfma_f32_16x16x32_bf16 v[6:9], v[188:191], v[248:251], v[6:9]
	v_mfma_f32_16x16x32_bf16 v[22:25], v[188:191], v[252:255], v[22:25]
	ds_read_b128 v[188:191], v130 offset:37888
	v_mfma_f32_16x16x32_bf16 v[50:53], v[192:195], v[240:243], v[50:53]
	v_mfma_f32_16x16x32_bf16 v[26:29], v[192:195], v[244:247], v[26:29]
	v_mfma_f32_16x16x32_bf16 v[2:5], v[192:195], v[248:251], v[2:5]
	v_mfma_f32_16x16x32_bf16 v[14:17], v[192:195], v[252:255], v[14:17]
	ds_read_b128 v[192:195], v130 offset:39936
	s_waitcnt lgkmcnt(3)
	v_mfma_f32_16x16x32_bf16 v[126:129], v[180:183], v[164:167], v[126:129]
	v_mfma_f32_16x16x32_bf16 v[110:113], v[180:183], v[168:171], v[110:113]
	v_mfma_f32_16x16x32_bf16 v[94:97], v[180:183], v[172:175], v[94:97]
	v_mfma_f32_16x16x32_bf16 v[78:81], v[180:183], v[176:179], v[78:81]
	ds_read_b128 v[240:243], v199 offset:1024
	ds_read_b128 v[244:247], v200 offset:1024
	s_waitcnt lgkmcnt(4)
	v_mfma_f32_16x16x32_bf16 v[122:125], v[184:187], v[164:167], v[122:125]
	v_mfma_f32_16x16x32_bf16 v[106:109], v[184:187], v[168:171], v[106:109]
	v_mfma_f32_16x16x32_bf16 v[90:93], v[184:187], v[172:175], v[90:93]
	v_mfma_f32_16x16x32_bf16 v[74:77], v[184:187], v[176:179], v[74:77]
	ds_read_b128 v[248:251], v201 offset:1024
	ds_read_b128 v[252:255], v202 offset:1024
	s_waitcnt lgkmcnt(5)
	v_mfma_f32_16x16x32_bf16 v[118:121], v[188:191], v[164:167], v[118:121]
	v_mfma_f32_16x16x32_bf16 v[102:105], v[188:191], v[168:171], v[102:105]
	v_mfma_f32_16x16x32_bf16 v[86:89], v[188:191], v[172:175], v[86:89]
	v_mfma_f32_16x16x32_bf16 v[70:73], v[188:191], v[176:179], v[70:73]
	s_waitcnt lgkmcnt(4)
	v_mfma_f32_16x16x32_bf16 v[114:117], v[192:195], v[164:167], v[114:117]
	v_mfma_f32_16x16x32_bf16 v[98:101], v[192:195], v[168:171], v[98:101]
	v_mfma_f32_16x16x32_bf16 v[82:85], v[192:195], v[172:175], v[82:85]
	v_mfma_f32_16x16x32_bf16 v[66:69], v[192:195], v[176:179], v[66:69]
	s_waitcnt vmcnt(0) lgkmcnt(0)
	s_barrier
	s_add_i32 s101, s100, s31
	v_mfma_f32_16x16x32_bf16 v[62:65], v[180:183], v[240:243], v[62:65]
	v_mfma_f32_16x16x32_bf16 v[46:49], v[180:183], v[244:247], v[46:49]
	v_mfma_f32_16x16x32_bf16 v[18:21], v[180:183], v[248:251], v[18:21]
	v_mfma_f32_16x16x32_bf16 v[38:41], v[180:183], v[252:255], v[38:41]
	v_add3_u32 v130, s42, v152, v153
	ds_read_b128 v[180:183], v130 offset:32768
	v_add3_u32 v163, s42, v152, v154
	v_add3_u32 v196, s42, v156, v155
	v_add3_u32 v197, s42, v156, v157
	v_add3_u32 v198, s42, v156, v158
	ds_read_b128 v[164:167], v163
	ds_read_b128 v[168:171], v196
	ds_read_b128 v[172:175], v197
	ds_read_b128 v[176:179], v198
	s_cmpk_eq_i32 s38, 0x700
	s_cbranch_scc1 .Lpk_793_0
	s_mov_b32 m0, s101
	v_lshl_add_u64 v[148:149], v[148:149], 0, s[98:99]
	global_load_lds_dwordx4 v[148:149], off
.Lpk_793_0:
	v_mfma_f32_16x16x32_bf16 v[58:61], v[184:187], v[240:243], v[58:61]
	v_mfma_f32_16x16x32_bf16 v[42:45], v[184:187], v[244:247], v[42:45]
	v_mfma_f32_16x16x32_bf16 v[10:13], v[184:187], v[248:251], v[10:13]
	v_mfma_f32_16x16x32_bf16 v[30:33], v[184:187], v[252:255], v[30:33]
	ds_read_b128 v[184:187], v130 offset:34816
	v_add3_u32 v199, s42, v156, v159
	v_add3_u32 v200, s42, v156, v160
	v_add3_u32 v201, s42, v156, v161
	v_add3_u32 v202, s42, v156, v162
	s_cmpk_eq_i32 s38, 0x700
	s_cbranch_scc1 .Lpk_793_1
	s_add_i32 m0, s101, 0x8000
	v_lshl_add_u64 v[140:141], v[140:141], 0, s[98:99]
	global_load_lds_dwordx4 v[140:141], off
.Lpk_793_1:
	v_mfma_f32_16x16x32_bf16 v[54:57], v[188:191], v[240:243], v[54:57]
	v_mfma_f32_16x16x32_bf16 v[34:37], v[188:191], v[244:247], v[34:37]
	v_mfma_f32_16x16x32_bf16 v[6:9], v[188:191], v[248:251], v[6:9]
	v_mfma_f32_16x16x32_bf16 v[22:25], v[188:191], v[252:255], v[22:25]
	ds_read_b128 v[188:191], v130 offset:36864
	s_cmpk_eq_i32 s38, 0x700
	s_cbranch_scc1 .Lpk_793_2
	s_add_i32 m0, s101, 0x2000
	v_lshl_add_u64 v[146:147], v[146:147], 0, s[98:99]
	global_load_lds_dwordx4 v[146:147], off
.Lpk_793_2:
	v_mfma_f32_16x16x32_bf16 v[50:53], v[192:195], v[240:243], v[50:53]
	v_mfma_f32_16x16x32_bf16 v[26:29], v[192:195], v[244:247], v[26:29]
	v_mfma_f32_16x16x32_bf16 v[2:5], v[192:195], v[248:251], v[2:5]
	v_mfma_f32_16x16x32_bf16 v[14:17], v[192:195], v[252:255], v[14:17]
	ds_read_b128 v[192:195], v130 offset:38912
	s_cmpk_eq_i32 s38, 0x700
	s_cbranch_scc1 .Lpk_793_3
	s_add_i32 m0, s101, 0xa000
	v_lshl_add_u64 v[138:139], v[138:139], 0, s[98:99]
	global_load_lds_dwordx4 v[138:139], off

.LBB0_795:
	s_and_b32 s0, s29, 0x10000
	s_xor_b32 s53, s0, 0x10000
	s_add_i32 s0, s0, 0
	s_add_i32 s101, s100, s53
	s_waitcnt lgkmcnt(3)
	v_mfma_f32_16x16x32_bf16 v[124:127], v[180:183], v[164:167], v[124:127]
	v_mfma_f32_16x16x32_bf16 v[108:111], v[180:183], v[168:171], v[108:111]
	v_mfma_f32_16x16x32_bf16 v[92:95], v[180:183], v[172:175], v[92:95]
	v_mfma_f32_16x16x32_bf16 v[76:79], v[180:183], v[176:179], v[76:79]
	ds_read_b128 v[240:243], v199
	ds_read_b128 v[244:247], v200
	s_cmpk_eq_i32 s42, 0
	s_cbranch_scc1 .Lpk_795_4
	s_add_i32 m0, s101, 0x4000
	v_lshl_add_u64 v[144:145], v[144:145], 0, s[98:99]
	global_load_lds_dwordx4 v[144:145], off
.Lpk_795_4:
	s_waitcnt lgkmcnt(4)
	v_mfma_f32_16x16x32_bf16 v[120:123], v[184:187], v[164:167], v[120:123]
	v_mfma_f32_16x16x32_bf16 v[104:107], v[184:187], v[168:171], v[104:107]
	v_mfma_f32_16x16x32_bf16 v[88:91], v[184:187], v[172:175], v[88:91]
	v_mfma_f32_16x16x32_bf16 v[72:75], v[184:187], v[176:179], v[72:75]
	ds_read_b128 v[248:251], v201
	ds_read_b128 v[252:255], v202
	s_cmpk_eq_i32 s42, 0
	s_cbranch_scc1 .Lpk_795_5
	s_add_i32 m0, s101, 0xc000
	v_lshl_add_u64 v[136:137], v[136:137], 0, s[98:99]
	global_load_lds_dwordx4 v[136:137], off
.Lpk_795_5:
	s_waitcnt lgkmcnt(5)
	v_mfma_f32_16x16x32_bf16 v[116:119], v[188:191], v[164:167], v[116:119]
	v_mfma_f32_16x16x32_bf16 v[100:103], v[188:191], v[168:171], v[100:103]
	v_mfma_f32_16x16x32_bf16 v[84:87], v[188:191], v[172:175], v[84:87]
	v_mfma_f32_16x16x32_bf16 v[68:71], v[188:191], v[176:179], v[68:71]
	s_cmpk_eq_i32 s42, 0
	s_cbranch_scc1 .Lpk_795_6
	s_add_i32 m0, s101, 0x6000
	v_lshl_add_u64 v[142:143], v[142:143], 0, s[98:99]
	global_load_lds_dwordx4 v[142:143], off
.Lpk_795_6:
	s_waitcnt lgkmcnt(4)
	v_mfma_f32_16x16x32_bf16 v[112:115], v[192:195], v[164:167], v[112:115]
	v_mfma_f32_16x16x32_bf16 v[96:99], v[192:195], v[168:171], v[96:99]
	v_mfma_f32_16x16x32_bf16 v[80:83], v[192:195], v[172:175], v[80:83]
	v_mfma_f32_16x16x32_bf16 v[64:67], v[192:195], v[176:179], v[64:67]
	s_cmpk_eq_i32 s42, 0
	s_cbranch_scc1 .Lpk_795_7
	s_add_i32 m0, s101, 0xe000
	v_lshl_add_u64 v[134:135], v[134:135], 0, s[98:99]
	global_load_lds_dwordx4 v[134:135], off
.Lpk_795_7:
	ds_read_b128 v[164:167], v163 offset:1024
	ds_read_b128 v[168:171], v196 offset:1024
	ds_read_b128 v[172:175], v197 offset:1024
	ds_read_b128 v[176:179], v198 offset:1024
	s_waitcnt lgkmcnt(4)
	v_mfma_f32_16x16x32_bf16 v[60:63], v[180:183], v[240:243], v[60:63]
	v_mfma_f32_16x16x32_bf16 v[44:47], v[180:183], v[244:247], v[44:47]
	v_mfma_f32_16x16x32_bf16 v[16:19], v[180:183], v[248:251], v[16:19]
	v_mfma_f32_16x16x32_bf16 v[36:39], v[180:183], v[252:255], v[36:39]
	ds_read_b128 v[180:183], v130 offset:33792
	v_mfma_f32_16x16x32_bf16 v[56:59], v[184:187], v[240:243], v[56:59]
	v_mfma_f32_16x16x32_bf16 v[40:43], v[184:187], v[244:247], v[40:43]
	v_mfma_f32_16x16x32_bf16 v[12:15], v[184:187], v[248:251], v[12:15]
	v_mfma_f32_16x16x32_bf16 v[28:31], v[184:187], v[252:255], v[28:31]
	ds_read_b128 v[184:187], v130 offset:35840
	v_mfma_f32_16x16x32_bf16 v[52:55], v[188:191], v[240:243], v[52:55]
	v_mfma_f32_16x16x32_bf16 v[32:35], v[188:191], v[244:247], v[32:35]
	v_mfma_f32_16x16x32_bf16 v[4:7], v[188:191], v[248:251], v[4:7]
	v_mfma_f32_16x16x32_bf16 v[20:23], v[188:191], v[252:255], v[20:23]
	ds_read_b128 v[188:191], v130 offset:37888
	v_mfma_f32_16x16x32_bf16 v[48:51], v[192:195], v[240:243], v[48:51]
	v_mfma_f32_16x16x32_bf16 v[24:27], v[192:195], v[244:247], v[24:27]
	v_mfma_f32_16x16x32_bf16 v[0:3], v[192:195], v[248:251], v[0:3]
	v_mfma_f32_16x16x32_bf16 v[8:11], v[192:195], v[252:255], v[8:11]
	ds_read_b128 v[192:195], v130 offset:39936
	s_waitcnt lgkmcnt(3)
	v_mfma_f32_16x16x32_bf16 v[124:127], v[180:183], v[164:167], v[124:127]
	v_mfma_f32_16x16x32_bf16 v[108:111], v[180:183], v[168:171], v[108:111]
	v_mfma_f32_16x16x32_bf16 v[92:95], v[180:183], v[172:175], v[92:95]
	v_mfma_f32_16x16x32_bf16 v[76:79], v[180:183], v[176:179], v[76:79]
	ds_read_b128 v[240:243], v199 offset:1024
	ds_read_b128 v[244:247], v200 offset:1024
	s_waitcnt lgkmcnt(4)
	v_mfma_f32_16x16x32_bf16 v[120:123], v[184:187], v[164:167], v[120:123]
	v_mfma_f32_16x16x32_bf16 v[104:107], v[184:187], v[168:171], v[104:107]
	v_mfma_f32_16x16x32_bf16 v[88:91], v[184:187], v[172:175], v[88:91]
	v_mfma_f32_16x16x32_bf16 v[72:75], v[184:187], v[176:179], v[72:75]
	ds_read_b128 v[248:251], v201 offset:1024
	ds_read_b128 v[252:255], v202 offset:1024
	s_waitcnt lgkmcnt(5)
	v_mfma_f32_16x16x32_bf16 v[116:119], v[188:191], v[164:167], v[116:119]
	v_mfma_f32_16x16x32_bf16 v[100:103], v[188:191], v[168:171], v[100:103]
	v_mfma_f32_16x16x32_bf16 v[84:87], v[188:191], v[172:175], v[84:87]
	v_mfma_f32_16x16x32_bf16 v[68:71], v[188:191], v[176:179], v[68:71]
	s_waitcnt lgkmcnt(4)
	v_mfma_f32_16x16x32_bf16 v[112:115], v[192:195], v[164:167], v[112:115]
	v_mfma_f32_16x16x32_bf16 v[96:99], v[192:195], v[168:171], v[96:99]
	v_mfma_f32_16x16x32_bf16 v[80:83], v[192:195], v[172:175], v[80:83]
	v_mfma_f32_16x16x32_bf16 v[64:67], v[192:195], v[176:179], v[64:67]
	s_waitcnt vmcnt(0) lgkmcnt(0)
	s_barrier
	s_add_i32 s101, s100, s0
	v_mfma_f32_16x16x32_bf16 v[60:63], v[180:183], v[240:243], v[60:63]
	v_mfma_f32_16x16x32_bf16 v[44:47], v[180:183], v[244:247], v[44:47]
	v_mfma_f32_16x16x32_bf16 v[16:19], v[180:183], v[248:251], v[16:19]
	v_mfma_f32_16x16x32_bf16 v[36:39], v[180:183], v[252:255], v[36:39]
	v_add3_u32 v130, s53, v152, v153
	ds_read_b128 v[180:183], v130 offset:32768
	v_add3_u32 v163, s53, v152, v154
	v_add3_u32 v196, s53, v156, v155
	v_add3_u32 v197, s53, v156, v157
	v_add3_u32 v198, s53, v156, v158
	ds_read_b128 v[164:167], v163
	ds_read_b128 v[168:171], v196
	ds_read_b128 v[172:175], v197
	ds_read_b128 v[176:179], v198
	s_cmpk_eq_i32 s42, 0x700
	s_cbranch_scc1 .Lpk_795_0
	s_mov_b32 m0, s101
	v_lshl_add_u64 v[148:149], v[148:149], 0, s[98:99]
	global_load_lds_dwordx4 v[148:149], off
.Lpk_795_0:
	v_mfma_f32_16x16x32_bf16 v[56:59], v[184:187], v[240:243], v[56:59]
	v_mfma_f32_16x16x32_bf16 v[40:43], v[184:187], v[244:247], v[40:43]
	v_mfma_f32_16x16x32_bf16 v[12:15], v[184:187], v[248:251], v[12:15]
	v_mfma_f32_16x16x32_bf16 v[28:31], v[184:187], v[252:255], v[28:31]
	ds_read_b128 v[184:187], v130 offset:34816
	v_add3_u32 v199, s53, v156, v159
	v_add3_u32 v200, s53, v156, v160
	v_add3_u32 v201, s53, v156, v161
	v_add3_u32 v202, s53, v156, v162
	s_cmpk_eq_i32 s42, 0x700
	s_cbranch_scc1 .Lpk_795_1
	s_add_i32 m0, s101, 0x8000
	v_lshl_add_u64 v[140:141], v[140:141], 0, s[98:99]
	global_load_lds_dwordx4 v[140:141], off
.Lpk_795_1:
	v_mfma_f32_16x16x32_bf16 v[52:55], v[188:191], v[240:243], v[52:55]
	v_mfma_f32_16x16x32_bf16 v[32:35], v[188:191], v[244:247], v[32:35]
	v_mfma_f32_16x16x32_bf16 v[4:7], v[188:191], v[248:251], v[4:7]
	v_mfma_f32_16x16x32_bf16 v[20:23], v[188:191], v[252:255], v[20:23]
	ds_read_b128 v[188:191], v130 offset:36864
	s_cmpk_eq_i32 s42, 0x700
	s_cbranch_scc1 .Lpk_795_2
	s_add_i32 m0, s101, 0x2000
	v_lshl_add_u64 v[146:147], v[146:147], 0, s[98:99]
	global_load_lds_dwordx4 v[146:147], off
.Lpk_795_2:
	v_mfma_f32_16x16x32_bf16 v[48:51], v[192:195], v[240:243], v[48:51]
	v_mfma_f32_16x16x32_bf16 v[24:27], v[192:195], v[244:247], v[24:27]
	v_mfma_f32_16x16x32_bf16 v[0:3], v[192:195], v[248:251], v[0:3]
	v_mfma_f32_16x16x32_bf16 v[8:11], v[192:195], v[252:255], v[8:11]
	ds_read_b128 v[192:195], v130 offset:38912
	s_cmpk_eq_i32 s42, 0x700
	s_cbranch_scc1 .Lpk_795_3
	s_add_i32 m0, s101, 0xa000
	v_lshl_add_u64 v[138:139], v[138:139], 0, s[98:99]
	global_load_lds_dwordx4 v[138:139], off

.LBB0_797:
	s_and_b32 s39, s38, 0x10000
	s_xor_b32 s42, s39, 0x10000
	s_add_i32 s39, s39, 0
	s_add_i32 s101, s100, s42
	s_waitcnt lgkmcnt(3)
	v_mfma_f32_16x16x32_bf16 v[126:129], v[180:183], v[164:167], v[126:129]
	v_mfma_f32_16x16x32_bf16 v[110:113], v[180:183], v[168:171], v[110:113]
	v_mfma_f32_16x16x32_bf16 v[94:97], v[180:183], v[172:175], v[94:97]
	v_mfma_f32_16x16x32_bf16 v[78:81], v[180:183], v[176:179], v[78:81]
	ds_read_b128 v[240:243], v199
	ds_read_b128 v[244:247], v200
	s_cmpk_eq_i32 s36, 0
	s_cbranch_scc1 .Lpk_797_4
	s_add_i32 m0, s101, 0x4000
	v_lshl_add_u64 v[144:145], v[144:145], 0, s[98:99]
	global_load_lds_dwordx4 v[144:145], off
.Lpk_797_4:
	s_waitcnt lgkmcnt(4)
	v_mfma_f32_16x16x32_bf16 v[122:125], v[184:187], v[164:167], v[122:125]
	v_mfma_f32_16x16x32_bf16 v[106:109], v[184:187], v[168:171], v[106:109]
	v_mfma_f32_16x16x32_bf16 v[90:93], v[184:187], v[172:175], v[90:93]
	v_mfma_f32_16x16x32_bf16 v[74:77], v[184:187], v[176:179], v[74:77]
	ds_read_b128 v[248:251], v201
	ds_read_b128 v[252:255], v202
	s_cmpk_eq_i32 s36, 0
	s_cbranch_scc1 .Lpk_797_5
	s_add_i32 m0, s101, 0xc000
	v_lshl_add_u64 v[136:137], v[136:137], 0, s[98:99]
	global_load_lds_dwordx4 v[136:137], off
.Lpk_797_5:
	s_waitcnt lgkmcnt(5)
	v_mfma_f32_16x16x32_bf16 v[118:121], v[188:191], v[164:167], v[118:121]
	v_mfma_f32_16x16x32_bf16 v[102:105], v[188:191], v[168:171], v[102:105]
	v_mfma_f32_16x16x32_bf16 v[86:89], v[188:191], v[172:175], v[86:89]
	v_mfma_f32_16x16x32_bf16 v[70:73], v[188:191], v[176:179], v[70:73]
	s_cmpk_eq_i32 s36, 0
	s_cbranch_scc1 .Lpk_797_6
	s_add_i32 m0, s101, 0x6000
	v_lshl_add_u64 v[142:143], v[142:143], 0, s[98:99]
	global_load_lds_dwordx4 v[142:143], off
.Lpk_797_6:
	s_waitcnt lgkmcnt(4)
	v_mfma_f32_16x16x32_bf16 v[114:117], v[192:195], v[164:167], v[114:117]
	v_mfma_f32_16x16x32_bf16 v[98:101], v[192:195], v[168:171], v[98:101]
	v_mfma_f32_16x16x32_bf16 v[82:85], v[192:195], v[172:175], v[82:85]
	v_mfma_f32_16x16x32_bf16 v[66:69], v[192:195], v[176:179], v[66:69]
	s_cmpk_eq_i32 s36, 0
	s_cbranch_scc1 .Lpk_797_7
	s_add_i32 m0, s101, 0xe000
	v_lshl_add_u64 v[134:135], v[134:135], 0, s[98:99]
	global_load_lds_dwordx4 v[134:135], off
.Lpk_797_7:
	ds_read_b128 v[164:167], v163 offset:1024
	ds_read_b128 v[168:171], v196 offset:1024
	ds_read_b128 v[172:175], v197 offset:1024
	ds_read_b128 v[176:179], v198 offset:1024
	s_waitcnt lgkmcnt(4)
	v_mfma_f32_16x16x32_bf16 v[62:65], v[180:183], v[240:243], v[62:65]
	v_mfma_f32_16x16x32_bf16 v[46:49], v[180:183], v[244:247], v[46:49]
	v_mfma_f32_16x16x32_bf16 v[18:21], v[180:183], v[248:251], v[18:21]
	v_mfma_f32_16x16x32_bf16 v[38:41], v[180:183], v[252:255], v[38:41]
	ds_read_b128 v[180:183], v130 offset:33792
	v_mfma_f32_16x16x32_bf16 v[58:61], v[184:187], v[240:243], v[58:61]
	v_mfma_f32_16x16x32_bf16 v[42:45], v[184:187], v[244:247], v[42:45]
	v_mfma_f32_16x16x32_bf16 v[14:17], v[184:187], v[248:251], v[14:17]
	v_mfma_f32_16x16x32_bf16 v[30:33], v[184:187], v[252:255], v[30:33]
	ds_read_b128 v[184:187], v130 offset:35840
	v_mfma_f32_16x16x32_bf16 v[54:57], v[188:191], v[240:243], v[54:57]
	v_mfma_f32_16x16x32_bf16 v[34:37], v[188:191], v[244:247], v[34:37]
	v_mfma_f32_16x16x32_bf16 v[6:9], v[188:191], v[248:251], v[6:9]
	v_mfma_f32_16x16x32_bf16 v[22:25], v[188:191], v[252:255], v[22:25]
	ds_read_b128 v[188:191], v130 offset:37888
	v_mfma_f32_16x16x32_bf16 v[50:53], v[192:195], v[240:243], v[50:53]
	v_mfma_f32_16x16x32_bf16 v[26:29], v[192:195], v[244:247], v[26:29]
	v_mfma_f32_16x16x32_bf16 v[2:5], v[192:195], v[248:251], v[2:5]
	v_mfma_f32_16x16x32_bf16 v[10:13], v[192:195], v[252:255], v[10:13]
	ds_read_b128 v[192:195], v130 offset:39936
	s_waitcnt lgkmcnt(3)
	v_mfma_f32_16x16x32_bf16 v[126:129], v[180:183], v[164:167], v[126:129]
	v_mfma_f32_16x16x32_bf16 v[110:113], v[180:183], v[168:171], v[110:113]
	v_mfma_f32_16x16x32_bf16 v[94:97], v[180:183], v[172:175], v[94:97]
	v_mfma_f32_16x16x32_bf16 v[78:81], v[180:183], v[176:179], v[78:81]
	ds_read_b128 v[240:243], v199 offset:1024
	ds_read_b128 v[244:247], v200 offset:1024
	s_waitcnt lgkmcnt(4)
	v_mfma_f32_16x16x32_bf16 v[122:125], v[184:187], v[164:167], v[122:125]
	v_mfma_f32_16x16x32_bf16 v[106:109], v[184:187], v[168:171], v[106:109]
	v_mfma_f32_16x16x32_bf16 v[90:93], v[184:187], v[172:175], v[90:93]
	v_mfma_f32_16x16x32_bf16 v[74:77], v[184:187], v[176:179], v[74:77]
	ds_read_b128 v[248:251], v201 offset:1024
	ds_read_b128 v[252:255], v202 offset:1024
	s_waitcnt lgkmcnt(5)
	v_mfma_f32_16x16x32_bf16 v[118:121], v[188:191], v[164:167], v[118:121]
	v_mfma_f32_16x16x32_bf16 v[102:105], v[188:191], v[168:171], v[102:105]
	v_mfma_f32_16x16x32_bf16 v[86:89], v[188:191], v[172:175], v[86:89]
	v_mfma_f32_16x16x32_bf16 v[70:73], v[188:191], v[176:179], v[70:73]
	s_waitcnt lgkmcnt(4)
	v_mfma_f32_16x16x32_bf16 v[114:117], v[192:195], v[164:167], v[114:117]
	v_mfma_f32_16x16x32_bf16 v[98:101], v[192:195], v[168:171], v[98:101]
	v_mfma_f32_16x16x32_bf16 v[82:85], v[192:195], v[172:175], v[82:85]
	v_mfma_f32_16x16x32_bf16 v[66:69], v[192:195], v[176:179], v[66:69]
	s_waitcnt vmcnt(0) lgkmcnt(0)
	s_barrier
	s_add_i32 s101, s100, s39
	v_mfma_f32_16x16x32_bf16 v[62:65], v[180:183], v[240:243], v[62:65]
	v_mfma_f32_16x16x32_bf16 v[46:49], v[180:183], v[244:247], v[46:49]
	v_mfma_f32_16x16x32_bf16 v[18:21], v[180:183], v[248:251], v[18:21]
	v_mfma_f32_16x16x32_bf16 v[38:41], v[180:183], v[252:255], v[38:41]
	v_add3_u32 v130, s42, v152, v153
	ds_read_b128 v[180:183], v130 offset:32768
	v_add3_u32 v163, s42, v152, v154
	v_add3_u32 v196, s42, v156, v155
	v_add3_u32 v197, s42, v156, v157
	v_add3_u32 v198, s42, v156, v158
	ds_read_b128 v[164:167], v163
	ds_read_b128 v[168:171], v196
	ds_read_b128 v[172:175], v197
	ds_read_b128 v[176:179], v198
	s_cmpk_eq_i32 s36, 0x700
	s_cbranch_scc1 .Lpk_797_0
	s_mov_b32 m0, s101
	v_lshl_add_u64 v[148:149], v[148:149], 0, s[98:99]
	global_load_lds_dwordx4 v[148:149], off
.Lpk_797_0:
	v_mfma_f32_16x16x32_bf16 v[58:61], v[184:187], v[240:243], v[58:61]
	v_mfma_f32_16x16x32_bf16 v[42:45], v[184:187], v[244:247], v[42:45]
	v_mfma_f32_16x16x32_bf16 v[14:17], v[184:187], v[248:251], v[14:17]
	v_mfma_f32_16x16x32_bf16 v[30:33], v[184:187], v[252:255], v[30:33]
	ds_read_b128 v[184:187], v130 offset:34816
	v_add3_u32 v199, s42, v156, v159
	v_add3_u32 v200, s42, v156, v160
	v_add3_u32 v201, s42, v156, v161
	v_add3_u32 v202, s42, v156, v162
	s_cmpk_eq_i32 s36, 0x700
	s_cbranch_scc1 .Lpk_797_1
	s_add_i32 m0, s101, 0x8000
	v_lshl_add_u64 v[140:141], v[140:141], 0, s[98:99]
	global_load_lds_dwordx4 v[140:141], off
.Lpk_797_1:
	v_mfma_f32_16x16x32_bf16 v[54:57], v[188:191], v[240:243], v[54:57]
	v_mfma_f32_16x16x32_bf16 v[34:37], v[188:191], v[244:247], v[34:37]
	v_mfma_f32_16x16x32_bf16 v[6:9], v[188:191], v[248:251], v[6:9]
	v_mfma_f32_16x16x32_bf16 v[22:25], v[188:191], v[252:255], v[22:25]
	ds_read_b128 v[188:191], v130 offset:36864
	s_cmpk_eq_i32 s36, 0x700
	s_cbranch_scc1 .Lpk_797_2
	s_add_i32 m0, s101, 0x2000
	v_lshl_add_u64 v[146:147], v[146:147], 0, s[98:99]
	global_load_lds_dwordx4 v[146:147], off
.Lpk_797_2:
	v_mfma_f32_16x16x32_bf16 v[50:53], v[192:195], v[240:243], v[50:53]
	v_mfma_f32_16x16x32_bf16 v[26:29], v[192:195], v[244:247], v[26:29]
	v_mfma_f32_16x16x32_bf16 v[2:5], v[192:195], v[248:251], v[2:5]
	v_mfma_f32_16x16x32_bf16 v[10:13], v[192:195], v[252:255], v[10:13]
	ds_read_b128 v[192:195], v130 offset:38912
	s_cmpk_eq_i32 s36, 0x700
	s_cbranch_scc1 .Lpk_797_3
	s_add_i32 m0, s101, 0xa000
	v_lshl_add_u64 v[138:139], v[138:139], 0, s[98:99]
	global_load_lds_dwordx4 v[138:139], off

.LBB0_846:
	s_and_b32 s29, s15, 0x10000
	s_xor_b32 s30, s29, 0x10000
	s_add_i32 s29, s29, 0
	s_add_i32 s101, s100, s30
	s_waitcnt lgkmcnt(3)
	v_mfma_f32_16x16x32_bf16 v[124:127], v[178:181], v[162:165], v[124:127]
	v_mfma_f32_16x16x32_bf16 v[108:111], v[178:181], v[166:169], v[108:111]
	v_mfma_f32_16x16x32_bf16 v[92:95], v[178:181], v[170:173], v[92:95]
	v_mfma_f32_16x16x32_bf16 v[76:79], v[178:181], v[174:177], v[76:79]
	ds_read_b128 v[240:243], v197
	ds_read_b128 v[244:247], v198
	s_cmpk_eq_i32 s16, 0
	s_cbranch_scc1 .Lpk_846_4
	s_add_i32 m0, s101, 0x4000
	v_lshl_add_u64 v[142:143], v[142:143], 0, s[98:99]
	global_load_lds_dwordx4 v[142:143], off
.Lpk_846_4:
	s_waitcnt lgkmcnt(4)
	v_mfma_f32_16x16x32_bf16 v[120:123], v[182:185], v[162:165], v[120:123]
	v_mfma_f32_16x16x32_bf16 v[104:107], v[182:185], v[166:169], v[104:107]
	v_mfma_f32_16x16x32_bf16 v[88:91], v[182:185], v[170:173], v[88:91]
	v_mfma_f32_16x16x32_bf16 v[72:75], v[182:185], v[174:177], v[72:75]
	ds_read_b128 v[248:251], v199
	ds_read_b128 v[252:255], v200
	s_cmpk_eq_i32 s16, 0
	s_cbranch_scc1 .Lpk_846_5
	s_add_i32 m0, s101, 0xc000
	v_lshl_add_u64 v[134:135], v[134:135], 0, s[98:99]
	global_load_lds_dwordx4 v[134:135], off
.Lpk_846_5:
	s_waitcnt lgkmcnt(5)
	v_mfma_f32_16x16x32_bf16 v[116:119], v[186:189], v[162:165], v[116:119]
	v_mfma_f32_16x16x32_bf16 v[100:103], v[186:189], v[166:169], v[100:103]
	v_mfma_f32_16x16x32_bf16 v[84:87], v[186:189], v[170:173], v[84:87]
	v_mfma_f32_16x16x32_bf16 v[68:71], v[186:189], v[174:177], v[68:71]
	s_cmpk_eq_i32 s16, 0
	s_cbranch_scc1 .Lpk_846_6
	s_add_i32 m0, s101, 0x6000
	v_lshl_add_u64 v[140:141], v[140:141], 0, s[98:99]
	global_load_lds_dwordx4 v[140:141], off
.Lpk_846_6:
	s_waitcnt lgkmcnt(4)
	v_mfma_f32_16x16x32_bf16 v[112:115], v[190:193], v[162:165], v[112:115]
	v_mfma_f32_16x16x32_bf16 v[96:99], v[190:193], v[166:169], v[96:99]
	v_mfma_f32_16x16x32_bf16 v[80:83], v[190:193], v[170:173], v[80:83]
	v_mfma_f32_16x16x32_bf16 v[64:67], v[190:193], v[174:177], v[64:67]
	s_cmpk_eq_i32 s16, 0
	s_cbranch_scc1 .Lpk_846_7
	s_add_i32 m0, s101, 0xe000
	v_lshl_add_u64 v[130:131], v[130:131], 0, s[98:99]
	global_load_lds_dwordx4 v[130:131], off
.Lpk_846_7:
	ds_read_b128 v[162:165], v161 offset:1024
	ds_read_b128 v[166:169], v194 offset:1024
	ds_read_b128 v[170:173], v195 offset:1024
	ds_read_b128 v[174:177], v196 offset:1024
	s_waitcnt lgkmcnt(4)
	v_mfma_f32_16x16x32_bf16 v[60:63], v[178:181], v[240:243], v[60:63]
	v_mfma_f32_16x16x32_bf16 v[44:47], v[178:181], v[244:247], v[44:47]
	v_mfma_f32_16x16x32_bf16 v[16:19], v[178:181], v[248:251], v[16:19]
	v_mfma_f32_16x16x32_bf16 v[36:39], v[178:181], v[252:255], v[36:39]
	ds_read_b128 v[178:181], v128 offset:33792
	v_mfma_f32_16x16x32_bf16 v[56:59], v[182:185], v[240:243], v[56:59]
	v_mfma_f32_16x16x32_bf16 v[40:43], v[182:185], v[244:247], v[40:43]
	v_mfma_f32_16x16x32_bf16 v[8:11], v[182:185], v[248:251], v[8:11]
	v_mfma_f32_16x16x32_bf16 v[28:31], v[182:185], v[252:255], v[28:31]
	ds_read_b128 v[182:185], v128 offset:35840
	v_mfma_f32_16x16x32_bf16 v[52:55], v[186:189], v[240:243], v[52:55]
	v_mfma_f32_16x16x32_bf16 v[32:35], v[186:189], v[244:247], v[32:35]
	v_mfma_f32_16x16x32_bf16 v[4:7], v[186:189], v[248:251], v[4:7]
	v_mfma_f32_16x16x32_bf16 v[20:23], v[186:189], v[252:255], v[20:23]
	ds_read_b128 v[186:189], v128 offset:37888
	v_mfma_f32_16x16x32_bf16 v[48:51], v[190:193], v[240:243], v[48:51]
	v_mfma_f32_16x16x32_bf16 v[24:27], v[190:193], v[244:247], v[24:27]
	v_mfma_f32_16x16x32_bf16 v[0:3], v[190:193], v[248:251], v[0:3]
	v_mfma_f32_16x16x32_bf16 v[12:15], v[190:193], v[252:255], v[12:15]
	ds_read_b128 v[190:193], v128 offset:39936
	s_waitcnt lgkmcnt(3)
	v_mfma_f32_16x16x32_bf16 v[124:127], v[178:181], v[162:165], v[124:127]
	v_mfma_f32_16x16x32_bf16 v[108:111], v[178:181], v[166:169], v[108:111]
	v_mfma_f32_16x16x32_bf16 v[92:95], v[178:181], v[170:173], v[92:95]
	v_mfma_f32_16x16x32_bf16 v[76:79], v[178:181], v[174:177], v[76:79]
	ds_read_b128 v[240:243], v197 offset:1024
	ds_read_b128 v[244:247], v198 offset:1024
	s_waitcnt lgkmcnt(4)
	v_mfma_f32_16x16x32_bf16 v[120:123], v[182:185], v[162:165], v[120:123]
	v_mfma_f32_16x16x32_bf16 v[104:107], v[182:185], v[166:169], v[104:107]
	v_mfma_f32_16x16x32_bf16 v[88:91], v[182:185], v[170:173], v[88:91]
	v_mfma_f32_16x16x32_bf16 v[72:75], v[182:185], v[174:177], v[72:75]
	ds_read_b128 v[248:251], v199 offset:1024
	ds_read_b128 v[252:255], v200 offset:1024
	s_waitcnt lgkmcnt(5)
	v_mfma_f32_16x16x32_bf16 v[116:119], v[186:189], v[162:165], v[116:119]
	v_mfma_f32_16x16x32_bf16 v[100:103], v[186:189], v[166:169], v[100:103]
	v_mfma_f32_16x16x32_bf16 v[84:87], v[186:189], v[170:173], v[84:87]
	v_mfma_f32_16x16x32_bf16 v[68:71], v[186:189], v[174:177], v[68:71]
	s_waitcnt lgkmcnt(4)
	v_mfma_f32_16x16x32_bf16 v[112:115], v[190:193], v[162:165], v[112:115]
	v_mfma_f32_16x16x32_bf16 v[96:99], v[190:193], v[166:169], v[96:99]
	v_mfma_f32_16x16x32_bf16 v[80:83], v[190:193], v[170:173], v[80:83]
	v_mfma_f32_16x16x32_bf16 v[64:67], v[190:193], v[174:177], v[64:67]
	s_waitcnt vmcnt(0) lgkmcnt(0)
	s_barrier
	s_add_i32 s101, s100, s29
	v_mfma_f32_16x16x32_bf16 v[60:63], v[178:181], v[240:243], v[60:63]
	v_mfma_f32_16x16x32_bf16 v[44:47], v[178:181], v[244:247], v[44:47]
	v_mfma_f32_16x16x32_bf16 v[16:19], v[178:181], v[248:251], v[16:19]
	v_mfma_f32_16x16x32_bf16 v[36:39], v[178:181], v[252:255], v[36:39]
	v_add3_u32 v128, s30, v150, v151
	ds_read_b128 v[178:181], v128 offset:32768
	v_add3_u32 v161, s30, v150, v152
	v_add3_u32 v194, s30, v154, v153
	v_add3_u32 v195, s30, v154, v155
	v_add3_u32 v196, s30, v154, v156
	ds_read_b128 v[162:165], v161
	ds_read_b128 v[166:169], v194
	ds_read_b128 v[170:173], v195
	ds_read_b128 v[174:177], v196
	s_cmpk_eq_i32 s16, 0x700
	s_cbranch_scc1 .Lpk_846_0
	s_mov_b32 m0, s101
	v_lshl_add_u64 v[146:147], v[146:147], 0, s[98:99]
	global_load_lds_dwordx4 v[146:147], off
.Lpk_846_0:
	v_mfma_f32_16x16x32_bf16 v[56:59], v[182:185], v[240:243], v[56:59]
	v_mfma_f32_16x16x32_bf16 v[40:43], v[182:185], v[244:247], v[40:43]
	v_mfma_f32_16x16x32_bf16 v[8:11], v[182:185], v[248:251], v[8:11]
	v_mfma_f32_16x16x32_bf16 v[28:31], v[182:185], v[252:255], v[28:31]
	ds_read_b128 v[182:185], v128 offset:34816
	v_add3_u32 v197, s30, v154, v157
	v_add3_u32 v198, s30, v154, v158
	v_add3_u32 v199, s30, v154, v159
	v_add3_u32 v200, s30, v154, v160
	s_cmpk_eq_i32 s16, 0x700
	s_cbranch_scc1 .Lpk_846_1
	s_add_i32 m0, s101, 0x8000
	v_lshl_add_u64 v[138:139], v[138:139], 0, s[98:99]
	global_load_lds_dwordx4 v[138:139], off
.Lpk_846_1:
	v_mfma_f32_16x16x32_bf16 v[52:55], v[186:189], v[240:243], v[52:55]
	v_mfma_f32_16x16x32_bf16 v[32:35], v[186:189], v[244:247], v[32:35]
	v_mfma_f32_16x16x32_bf16 v[4:7], v[186:189], v[248:251], v[4:7]
	v_mfma_f32_16x16x32_bf16 v[20:23], v[186:189], v[252:255], v[20:23]
	ds_read_b128 v[186:189], v128 offset:36864
	s_cmpk_eq_i32 s16, 0x700
	s_cbranch_scc1 .Lpk_846_2
	s_add_i32 m0, s101, 0x2000
	v_lshl_add_u64 v[144:145], v[144:145], 0, s[98:99]
	global_load_lds_dwordx4 v[144:145], off
.Lpk_846_2:
	v_mfma_f32_16x16x32_bf16 v[48:51], v[190:193], v[240:243], v[48:51]
	v_mfma_f32_16x16x32_bf16 v[24:27], v[190:193], v[244:247], v[24:27]
	v_mfma_f32_16x16x32_bf16 v[0:3], v[190:193], v[248:251], v[0:3]
	v_mfma_f32_16x16x32_bf16 v[12:15], v[190:193], v[252:255], v[12:15]
	ds_read_b128 v[190:193], v128 offset:38912
	s_cmpk_eq_i32 s16, 0x700
	s_cbranch_scc1 .Lpk_846_3
	s_add_i32 m0, s101, 0xa000
	v_lshl_add_u64 v[136:137], v[136:137], 0, s[98:99]
	global_load_lds_dwordx4 v[136:137], off

.LBB0_942:
	s_and_b32 s17, s15, 0x10000
	s_xor_b32 s42, s17, 0x10000
	s_add_i32 s17, s17, 0
	s_add_i32 s101, s100, s42
	s_waitcnt lgkmcnt(3)
	v_mfma_f32_16x16x32_bf16 v[108:111], v[178:181], v[162:165], v[108:111]
	v_mfma_f32_16x16x32_bf16 v[92:95], v[178:181], v[166:169], v[92:95]
	v_mfma_f32_16x16x32_bf16 v[76:79], v[178:181], v[170:173], v[76:79]
	v_mfma_f32_16x16x32_bf16 v[60:63], v[178:181], v[174:177], v[60:63]
	ds_read_b128 v[240:243], v197
	ds_read_b128 v[244:247], v198
	s_cmpk_eq_i32 s18, 0
	s_cbranch_scc1 .Lpk_942_4
	s_add_i32 m0, s101, 0x4000
	v_lshl_add_u64 v[142:143], v[142:143], 0, s[98:99]
	global_load_lds_dwordx4 v[142:143], off
.Lpk_942_4:
	s_waitcnt lgkmcnt(4)
	v_mfma_f32_16x16x32_bf16 v[104:107], v[182:185], v[162:165], v[104:107]
	v_mfma_f32_16x16x32_bf16 v[88:91], v[182:185], v[166:169], v[88:91]
	v_mfma_f32_16x16x32_bf16 v[72:75], v[182:185], v[170:173], v[72:75]
	v_mfma_f32_16x16x32_bf16 v[56:59], v[182:185], v[174:177], v[56:59]
	ds_read_b128 v[248:251], v199
	ds_read_b128 v[252:255], v200
	s_cmpk_eq_i32 s18, 0
	s_cbranch_scc1 .Lpk_942_5
	s_add_i32 m0, s101, 0xc000
	v_lshl_add_u64 v[134:135], v[134:135], 0, s[98:99]
	global_load_lds_dwordx4 v[134:135], off
.Lpk_942_5:
	s_waitcnt lgkmcnt(5)
	v_mfma_f32_16x16x32_bf16 v[100:103], v[186:189], v[162:165], v[100:103]
	v_mfma_f32_16x16x32_bf16 v[84:87], v[186:189], v[166:169], v[84:87]
	v_mfma_f32_16x16x32_bf16 v[68:71], v[186:189], v[170:173], v[68:71]
	v_mfma_f32_16x16x32_bf16 v[52:55], v[186:189], v[174:177], v[52:55]
	s_cmpk_eq_i32 s18, 0
	s_cbranch_scc1 .Lpk_942_6
	s_add_i32 m0, s101, 0x6000
	v_lshl_add_u64 v[140:141], v[140:141], 0, s[98:99]
	global_load_lds_dwordx4 v[140:141], off
.Lpk_942_6:
	s_waitcnt lgkmcnt(4)
	v_mfma_f32_16x16x32_bf16 v[96:99], v[190:193], v[162:165], v[96:99]
	v_mfma_f32_16x16x32_bf16 v[80:83], v[190:193], v[166:169], v[80:83]
	v_mfma_f32_16x16x32_bf16 v[64:67], v[190:193], v[170:173], v[64:67]
	v_mfma_f32_16x16x32_bf16 v[48:51], v[190:193], v[174:177], v[48:51]
	s_cmpk_eq_i32 s18, 0
	s_cbranch_scc1 .Lpk_942_7
	s_add_i32 m0, s101, 0xe000
	v_lshl_add_u64 v[130:131], v[130:131], 0, s[98:99]
	global_load_lds_dwordx4 v[130:131], off
.Lpk_942_7:
	ds_read_b128 v[162:165], v161 offset:1024
	ds_read_b128 v[166:169], v194 offset:1024
	ds_read_b128 v[170:173], v195 offset:1024
	ds_read_b128 v[174:177], v196 offset:1024
	s_waitcnt lgkmcnt(4)
	v_mfma_f32_16x16x32_bf16 v[44:47], v[178:181], v[240:243], v[44:47]
	v_mfma_f32_16x16x32_bf16 v[28:31], v[178:181], v[244:247], v[28:31]
	v_mfma_f32_16x16x32_bf16 v[12:15], v[178:181], v[248:251], v[12:15]
	v_mfma_f32_16x16x32_bf16 v[112:115], v[178:181], v[252:255], v[112:115]
	ds_read_b128 v[178:181], v128 offset:33792
	v_mfma_f32_16x16x32_bf16 v[40:43], v[182:185], v[240:243], v[40:43]
	v_mfma_f32_16x16x32_bf16 v[24:27], v[182:185], v[244:247], v[24:27]
	v_mfma_f32_16x16x32_bf16 v[8:11], v[182:185], v[248:251], v[8:11]
	v_mfma_f32_16x16x32_bf16 v[116:119], v[182:185], v[252:255], v[116:119]
	ds_read_b128 v[182:185], v128 offset:35840
	v_mfma_f32_16x16x32_bf16 v[36:39], v[186:189], v[240:243], v[36:39]
	v_mfma_f32_16x16x32_bf16 v[20:23], v[186:189], v[244:247], v[20:23]
	v_mfma_f32_16x16x32_bf16 v[4:7], v[186:189], v[248:251], v[4:7]
	v_mfma_f32_16x16x32_bf16 v[120:123], v[186:189], v[252:255], v[120:123]
	ds_read_b128 v[186:189], v128 offset:37888
	v_mfma_f32_16x16x32_bf16 v[32:35], v[190:193], v[240:243], v[32:35]
	v_mfma_f32_16x16x32_bf16 v[16:19], v[190:193], v[244:247], v[16:19]
	v_mfma_f32_16x16x32_bf16 v[0:3], v[190:193], v[248:251], v[0:3]
	v_mfma_f32_16x16x32_bf16 v[124:127], v[190:193], v[252:255], v[124:127]
	ds_read_b128 v[190:193], v128 offset:39936
	s_waitcnt lgkmcnt(3)
	v_mfma_f32_16x16x32_bf16 v[108:111], v[178:181], v[162:165], v[108:111]
	v_mfma_f32_16x16x32_bf16 v[92:95], v[178:181], v[166:169], v[92:95]
	v_mfma_f32_16x16x32_bf16 v[76:79], v[178:181], v[170:173], v[76:79]
	v_mfma_f32_16x16x32_bf16 v[60:63], v[178:181], v[174:177], v[60:63]
	ds_read_b128 v[240:243], v197 offset:1024
	ds_read_b128 v[244:247], v198 offset:1024
	s_waitcnt lgkmcnt(4)
	v_mfma_f32_16x16x32_bf16 v[104:107], v[182:185], v[162:165], v[104:107]
	v_mfma_f32_16x16x32_bf16 v[88:91], v[182:185], v[166:169], v[88:91]
	v_mfma_f32_16x16x32_bf16 v[72:75], v[182:185], v[170:173], v[72:75]
	v_mfma_f32_16x16x32_bf16 v[56:59], v[182:185], v[174:177], v[56:59]
	ds_read_b128 v[248:251], v199 offset:1024
	ds_read_b128 v[252:255], v200 offset:1024
	s_waitcnt lgkmcnt(5)
	v_mfma_f32_16x16x32_bf16 v[100:103], v[186:189], v[162:165], v[100:103]
	v_mfma_f32_16x16x32_bf16 v[84:87], v[186:189], v[166:169], v[84:87]
	v_mfma_f32_16x16x32_bf16 v[68:71], v[186:189], v[170:173], v[68:71]
	v_mfma_f32_16x16x32_bf16 v[52:55], v[186:189], v[174:177], v[52:55]
	s_waitcnt lgkmcnt(4)
	v_mfma_f32_16x16x32_bf16 v[96:99], v[190:193], v[162:165], v[96:99]
	v_mfma_f32_16x16x32_bf16 v[80:83], v[190:193], v[166:169], v[80:83]
	v_mfma_f32_16x16x32_bf16 v[64:67], v[190:193], v[170:173], v[64:67]
	v_mfma_f32_16x16x32_bf16 v[48:51], v[190:193], v[174:177], v[48:51]
	s_waitcnt vmcnt(0) lgkmcnt(0)
	s_barrier
	s_add_i32 s101, s100, s17
	v_mfma_f32_16x16x32_bf16 v[44:47], v[178:181], v[240:243], v[44:47]
	v_mfma_f32_16x16x32_bf16 v[28:31], v[178:181], v[244:247], v[28:31]
	v_mfma_f32_16x16x32_bf16 v[12:15], v[178:181], v[248:251], v[12:15]
	v_mfma_f32_16x16x32_bf16 v[112:115], v[178:181], v[252:255], v[112:115]
	v_add3_u32 v128, s42, v150, v151
	ds_read_b128 v[178:181], v128 offset:32768
	v_add3_u32 v161, s42, v150, v152
	v_add3_u32 v194, s42, v154, v153
	v_add3_u32 v195, s42, v154, v155
	v_add3_u32 v196, s42, v154, v156
	ds_read_b128 v[162:165], v161
	ds_read_b128 v[166:169], v194
	ds_read_b128 v[170:173], v195
	ds_read_b128 v[174:177], v196
	s_cmpk_eq_i32 s18, 0x700
	s_cbranch_scc1 .Lpk_942_0
	s_mov_b32 m0, s101
	v_lshl_add_u64 v[146:147], v[146:147], 0, s[98:99]
	global_load_lds_dwordx4 v[146:147], off
.Lpk_942_0:
	v_mfma_f32_16x16x32_bf16 v[40:43], v[182:185], v[240:243], v[40:43]
	v_mfma_f32_16x16x32_bf16 v[24:27], v[182:185], v[244:247], v[24:27]
	v_mfma_f32_16x16x32_bf16 v[8:11], v[182:185], v[248:251], v[8:11]
	v_mfma_f32_16x16x32_bf16 v[116:119], v[182:185], v[252:255], v[116:119]
	ds_read_b128 v[182:185], v128 offset:34816
	v_add3_u32 v197, s42, v154, v157
	v_add3_u32 v198, s42, v154, v158
	v_add3_u32 v199, s42, v154, v159
	v_add3_u32 v200, s42, v154, v160
	s_cmpk_eq_i32 s18, 0x700
	s_cbranch_scc1 .Lpk_942_1
	s_add_i32 m0, s101, 0x8000
	v_lshl_add_u64 v[138:139], v[138:139], 0, s[98:99]
	global_load_lds_dwordx4 v[138:139], off
.Lpk_942_1:
	v_mfma_f32_16x16x32_bf16 v[36:39], v[186:189], v[240:243], v[36:39]
	v_mfma_f32_16x16x32_bf16 v[20:23], v[186:189], v[244:247], v[20:23]
	v_mfma_f32_16x16x32_bf16 v[4:7], v[186:189], v[248:251], v[4:7]
	v_mfma_f32_16x16x32_bf16 v[120:123], v[186:189], v[252:255], v[120:123]
	ds_read_b128 v[186:189], v128 offset:36864
	s_cmpk_eq_i32 s18, 0x700
	s_cbranch_scc1 .Lpk_942_2
	s_add_i32 m0, s101, 0x2000
	v_lshl_add_u64 v[144:145], v[144:145], 0, s[98:99]
	global_load_lds_dwordx4 v[144:145], off
.Lpk_942_2:
	v_mfma_f32_16x16x32_bf16 v[32:35], v[190:193], v[240:243], v[32:35]
	v_mfma_f32_16x16x32_bf16 v[16:19], v[190:193], v[244:247], v[16:19]
	v_mfma_f32_16x16x32_bf16 v[0:3], v[190:193], v[248:251], v[0:3]
	v_mfma_f32_16x16x32_bf16 v[124:127], v[190:193], v[252:255], v[124:127]
	ds_read_b128 v[190:193], v128 offset:38912
	s_cmpk_eq_i32 s18, 0x700
	s_cbranch_scc1 .Lpk_942_3
	s_add_i32 m0, s101, 0xa000
	v_lshl_add_u64 v[136:137], v[136:137], 0, s[98:99]
	global_load_lds_dwordx4 v[136:137], off

.LBB0_1040:
	s_and_b32 s17, s15, 0x10000
	s_xor_b32 s43, s17, 0x10000
	s_add_i32 s17, s17, 0
	s_add_i32 s101, s100, s43
	s_waitcnt lgkmcnt(3)
	v_mfma_f32_16x16x32_bf16 v[108:111], v[178:181], v[162:165], v[108:111]
	v_mfma_f32_16x16x32_bf16 v[92:95], v[178:181], v[166:169], v[92:95]
	v_mfma_f32_16x16x32_bf16 v[76:79], v[178:181], v[170:173], v[76:79]
	v_mfma_f32_16x16x32_bf16 v[60:63], v[178:181], v[174:177], v[60:63]
	ds_read_b128 v[240:243], v197
	ds_read_b128 v[244:247], v198
	s_cmpk_eq_i32 s18, 0
	s_cbranch_scc1 .Lpk_1040_4
	s_add_i32 m0, s101, 0x4000
	v_lshl_add_u64 v[142:143], v[142:143], 0, s[98:99]
	global_load_lds_dwordx4 v[142:143], off

.Lpk_1040_7:
	ds_read_b128 v[162:165], v161 offset:1024
	ds_read_b128 v[166:169], v194 offset:1024
	ds_read_b128 v[170:173], v195 offset:1024
	ds_read_b128 v[174:177], v196 offset:1024
	s_waitcnt lgkmcnt(4)
	v_mfma_f32_16x16x32_bf16 v[44:47], v[178:181], v[240:243], v[44:47]
	v_mfma_f32_16x16x32_bf16 v[28:31], v[178:181], v[244:247], v[28:31]
	v_mfma_f32_16x16x32_bf16 v[12:15], v[178:181], v[248:251], v[12:15]
	v_mfma_f32_16x16x32_bf16 v[112:115], v[178:181], v[252:255], v[112:115]
	ds_read_b128 v[178:181], v128 offset:33792
	v_mfma_f32_16x16x32_bf16 v[40:43], v[182:185], v[240:243], v[40:43]
	v_mfma_f32_16x16x32_bf16 v[24:27], v[182:185], v[244:247], v[24:27]
	v_mfma_f32_16x16x32_bf16 v[8:11], v[182:185], v[248:251], v[8:11]
	v_mfma_f32_16x16x32_bf16 v[116:119], v[182:185], v[252:255], v[116:119]
	ds_read_b128 v[182:185], v128 offset:35840
	v_mfma_f32_16x16x32_bf16 v[36:39], v[186:189], v[240:243], v[36:39]
	v_mfma_f32_16x16x32_bf16 v[20:23], v[186:189], v[244:247], v[20:23]
	v_mfma_f32_16x16x32_bf16 v[4:7], v[186:189], v[248:251], v[4:7]
	v_mfma_f32_16x16x32_bf16 v[120:123], v[186:189], v[252:255], v[120:123]
	ds_read_b128 v[186:189], v128 offset:37888
	v_mfma_f32_16x16x32_bf16 v[32:35], v[190:193], v[240:243], v[32:35]
	v_mfma_f32_16x16x32_bf16 v[16:19], v[190:193], v[244:247], v[16:19]
	v_mfma_f32_16x16x32_bf16 v[0:3], v[190:193], v[248:251], v[0:3]
	v_mfma_f32_16x16x32_bf16 v[124:127], v[190:193], v[252:255], v[124:127]
	ds_read_b128 v[190:193], v128 offset:39936
	s_waitcnt lgkmcnt(3)
	v_mfma_f32_16x16x32_bf16 v[108:111], v[178:181], v[162:165], v[108:111]
	v_mfma_f32_16x16x32_bf16 v[92:95], v[178:181], v[166:169], v[92:95]
	v_mfma_f32_16x16x32_bf16 v[76:79], v[178:181], v[170:173], v[76:79]
	v_mfma_f32_16x16x32_bf16 v[60:63], v[178:181], v[174:177], v[60:63]
	ds_read_b128 v[240:243], v197 offset:1024
	ds_read_b128 v[244:247], v198 offset:1024
	s_waitcnt lgkmcnt(4)
	v_mfma_f32_16x16x32_bf16 v[104:107], v[182:185], v[162:165], v[104:107]
	v_mfma_f32_16x16x32_bf16 v[88:91], v[182:185], v[166:169], v[88:91]
	v_mfma_f32_16x16x32_bf16 v[72:75], v[182:185], v[170:173], v[72:75]
	v_mfma_f32_16x16x32_bf16 v[56:59], v[182:185], v[174:177], v[56:59]
	ds_read_b128 v[248:251], v199 offset:1024
	ds_read_b128 v[252:255], v200 offset:1024
	s_waitcnt lgkmcnt(5)
	v_mfma_f32_16x16x32_bf16 v[100:103], v[186:189], v[162:165], v[100:103]
	v_mfma_f32_16x16x32_bf16 v[84:87], v[186:189], v[166:169], v[84:87]
	v_mfma_f32_16x16x32_bf16 v[68:71], v[186:189], v[170:173], v[68:71]
	v_mfma_f32_16x16x32_bf16 v[52:55], v[186:189], v[174:177], v[52:55]
	s_waitcnt lgkmcnt(4)
	v_mfma_f32_16x16x32_bf16 v[96:99], v[190:193], v[162:165], v[96:99]
	v_mfma_f32_16x16x32_bf16 v[80:83], v[190:193], v[166:169], v[80:83]
	v_mfma_f32_16x16x32_bf16 v[64:67], v[190:193], v[170:173], v[64:67]
	v_mfma_f32_16x16x32_bf16 v[48:51], v[190:193], v[174:177], v[48:51]
	s_waitcnt vmcnt(0) lgkmcnt(0)
	s_barrier
	s_add_i32 s101, s100, s17
	v_mfma_f32_16x16x32_bf16 v[44:47], v[178:181], v[240:243], v[44:47]
	v_mfma_f32_16x16x32_bf16 v[28:31], v[178:181], v[244:247], v[28:31]
	v_mfma_f32_16x16x32_bf16 v[12:15], v[178:181], v[248:251], v[12:15]
	v_mfma_f32_16x16x32_bf16 v[112:115], v[178:181], v[252:255], v[112:115]
	v_add3_u32 v128, s43, v150, v151
	ds_read_b128 v[178:181], v128 offset:32768
	v_add3_u32 v161, s43, v150, v152
	v_add3_u32 v194, s43, v154, v153
	v_add3_u32 v195, s43, v154, v155
	v_add3_u32 v196, s43, v154, v156
	ds_read_b128 v[162:165], v161
	ds_read_b128 v[166:169], v194
	ds_read_b128 v[170:173], v195
	ds_read_b128 v[174:177], v196
	s_cmpk_eq_i32 s18, 0x700
	s_cbranch_scc1 .Lpk_1040_0
	s_mov_b32 m0, s101
	v_lshl_add_u64 v[146:147], v[146:147], 0, s[98:99]
	global_load_lds_dwordx4 v[146:147], off
.Lpk_1040_0:
	v_mfma_f32_16x16x32_bf16 v[40:43], v[182:185], v[240:243], v[40:43]
	v_mfma_f32_16x16x32_bf16 v[24:27], v[182:185], v[244:247], v[24:27]
	v_mfma_f32_16x16x32_bf16 v[8:11], v[182:185], v[248:251], v[8:11]
	v_mfma_f32_16x16x32_bf16 v[116:119], v[182:185], v[252:255], v[116:119]
	ds_read_b128 v[182:185], v128 offset:34816
	v_add3_u32 v197, s43, v154, v157
	v_add3_u32 v198, s43, v154, v158
	v_add3_u32 v199, s43, v154, v159
	v_add3_u32 v200, s43, v154, v160
	s_cmpk_eq_i32 s18, 0x700
	s_cbranch_scc1 .Lpk_1040_1
	s_add_i32 m0, s101, 0x8000
	v_lshl_add_u64 v[138:139], v[138:139], 0, s[98:99]
	global_load_lds_dwordx4 v[138:139], off

.LBB0_1138:
	s_and_b32 s27, s26, 0x10000
	s_xor_b32 s28, s27, 0x10000
	s_add_i32 s27, s27, 0
	s_add_i32 s101, s100, s28
	s_waitcnt lgkmcnt(3)
	v_mfma_f32_16x16x32_bf16 v[124:127], v[178:181], v[162:165], v[124:127]
	v_mfma_f32_16x16x32_bf16 v[108:111], v[178:181], v[166:169], v[108:111]
	v_mfma_f32_16x16x32_bf16 v[92:95], v[178:181], v[170:173], v[92:95]
	v_mfma_f32_16x16x32_bf16 v[76:79], v[178:181], v[174:177], v[76:79]
	ds_read_b128 v[240:243], v197
	ds_read_b128 v[244:247], v198
	s_cmpk_eq_i32 s12, 0
	s_cbranch_scc1 .Lpk_1138_4
	s_add_i32 m0, s101, 0x4000
	v_lshl_add_u64 v[142:143], v[142:143], 0, s[98:99]
	global_load_lds_dwordx4 v[142:143], off
.Lpk_1138_4:
	s_waitcnt lgkmcnt(4)
	v_mfma_f32_16x16x32_bf16 v[120:123], v[182:185], v[162:165], v[120:123]
	v_mfma_f32_16x16x32_bf16 v[104:107], v[182:185], v[166:169], v[104:107]
	v_mfma_f32_16x16x32_bf16 v[88:91], v[182:185], v[170:173], v[88:91]
	v_mfma_f32_16x16x32_bf16 v[72:75], v[182:185], v[174:177], v[72:75]
	ds_read_b128 v[248:251], v199
	ds_read_b128 v[252:255], v200
	s_cmpk_eq_i32 s12, 0
	s_cbranch_scc1 .Lpk_1138_5
	s_add_i32 m0, s101, 0xc000
	v_lshl_add_u64 v[134:135], v[134:135], 0, s[98:99]
	global_load_lds_dwordx4 v[134:135], off
.Lpk_1138_5:
	s_waitcnt lgkmcnt(5)
	v_mfma_f32_16x16x32_bf16 v[116:119], v[186:189], v[162:165], v[116:119]
	v_mfma_f32_16x16x32_bf16 v[100:103], v[186:189], v[166:169], v[100:103]
	v_mfma_f32_16x16x32_bf16 v[84:87], v[186:189], v[170:173], v[84:87]
	v_mfma_f32_16x16x32_bf16 v[68:71], v[186:189], v[174:177], v[68:71]
	s_cmpk_eq_i32 s12, 0
	s_cbranch_scc1 .Lpk_1138_6
	s_add_i32 m0, s101, 0x6000
	v_lshl_add_u64 v[140:141], v[140:141], 0, s[98:99]
	global_load_lds_dwordx4 v[140:141], off
.Lpk_1138_6:
	s_waitcnt lgkmcnt(4)
	v_mfma_f32_16x16x32_bf16 v[112:115], v[190:193], v[162:165], v[112:115]
	v_mfma_f32_16x16x32_bf16 v[96:99], v[190:193], v[166:169], v[96:99]
	v_mfma_f32_16x16x32_bf16 v[80:83], v[190:193], v[170:173], v[80:83]
	v_mfma_f32_16x16x32_bf16 v[64:67], v[190:193], v[174:177], v[64:67]
	s_cmpk_eq_i32 s12, 0
	s_cbranch_scc1 .Lpk_1138_7
	s_add_i32 m0, s101, 0xe000
	v_lshl_add_u64 v[130:131], v[130:131], 0, s[98:99]
	global_load_lds_dwordx4 v[130:131], off
.Lpk_1138_7:
	ds_read_b128 v[162:165], v161 offset:1024
	ds_read_b128 v[166:169], v194 offset:1024
	ds_read_b128 v[170:173], v195 offset:1024
	ds_read_b128 v[174:177], v196 offset:1024
	s_waitcnt lgkmcnt(4)
	v_mfma_f32_16x16x32_bf16 v[60:63], v[178:181], v[240:243], v[60:63]
	v_mfma_f32_16x16x32_bf16 v[44:47], v[178:181], v[244:247], v[44:47]
	v_mfma_f32_16x16x32_bf16 v[16:19], v[178:181], v[248:251], v[16:19]
	v_mfma_f32_16x16x32_bf16 v[36:39], v[178:181], v[252:255], v[36:39]
	ds_read_b128 v[178:181], v128 offset:33792
	v_mfma_f32_16x16x32_bf16 v[56:59], v[182:185], v[240:243], v[56:59]
	v_mfma_f32_16x16x32_bf16 v[40:43], v[182:185], v[244:247], v[40:43]
	v_mfma_f32_16x16x32_bf16 v[8:11], v[182:185], v[248:251], v[8:11]
	v_mfma_f32_16x16x32_bf16 v[28:31], v[182:185], v[252:255], v[28:31]
	ds_read_b128 v[182:185], v128 offset:35840
	v_mfma_f32_16x16x32_bf16 v[52:55], v[186:189], v[240:243], v[52:55]
	v_mfma_f32_16x16x32_bf16 v[32:35], v[186:189], v[244:247], v[32:35]
	v_mfma_f32_16x16x32_bf16 v[4:7], v[186:189], v[248:251], v[4:7]
	v_mfma_f32_16x16x32_bf16 v[20:23], v[186:189], v[252:255], v[20:23]
	ds_read_b128 v[186:189], v128 offset:37888
	v_mfma_f32_16x16x32_bf16 v[48:51], v[190:193], v[240:243], v[48:51]
	v_mfma_f32_16x16x32_bf16 v[24:27], v[190:193], v[244:247], v[24:27]
	v_mfma_f32_16x16x32_bf16 v[0:3], v[190:193], v[248:251], v[0:3]
	v_mfma_f32_16x16x32_bf16 v[12:15], v[190:193], v[252:255], v[12:15]
	ds_read_b128 v[190:193], v128 offset:39936
	s_waitcnt lgkmcnt(3)
	v_mfma_f32_16x16x32_bf16 v[124:127], v[178:181], v[162:165], v[124:127]
	v_mfma_f32_16x16x32_bf16 v[108:111], v[178:181], v[166:169], v[108:111]
	v_mfma_f32_16x16x32_bf16 v[92:95], v[178:181], v[170:173], v[92:95]
	v_mfma_f32_16x16x32_bf16 v[76:79], v[178:181], v[174:177], v[76:79]
	ds_read_b128 v[240:243], v197 offset:1024
	ds_read_b128 v[244:247], v198 offset:1024
	s_waitcnt lgkmcnt(4)
	v_mfma_f32_16x16x32_bf16 v[120:123], v[182:185], v[162:165], v[120:123]
	v_mfma_f32_16x16x32_bf16 v[104:107], v[182:185], v[166:169], v[104:107]
	v_mfma_f32_16x16x32_bf16 v[88:91], v[182:185], v[170:173], v[88:91]
	v_mfma_f32_16x16x32_bf16 v[72:75], v[182:185], v[174:177], v[72:75]
	ds_read_b128 v[248:251], v199 offset:1024
	ds_read_b128 v[252:255], v200 offset:1024
	s_waitcnt lgkmcnt(5)
	v_mfma_f32_16x16x32_bf16 v[116:119], v[186:189], v[162:165], v[116:119]
	v_mfma_f32_16x16x32_bf16 v[100:103], v[186:189], v[166:169], v[100:103]
	v_mfma_f32_16x16x32_bf16 v[84:87], v[186:189], v[170:173], v[84:87]
	v_mfma_f32_16x16x32_bf16 v[68:71], v[186:189], v[174:177], v[68:71]
	s_waitcnt lgkmcnt(4)
	v_mfma_f32_16x16x32_bf16 v[112:115], v[190:193], v[162:165], v[112:115]
	v_mfma_f32_16x16x32_bf16 v[96:99], v[190:193], v[166:169], v[96:99]
	v_mfma_f32_16x16x32_bf16 v[80:83], v[190:193], v[170:173], v[80:83]
	v_mfma_f32_16x16x32_bf16 v[64:67], v[190:193], v[174:177], v[64:67]
	s_waitcnt vmcnt(0) lgkmcnt(0)
	s_barrier
	s_add_i32 s101, s100, s27
	v_mfma_f32_16x16x32_bf16 v[60:63], v[178:181], v[240:243], v[60:63]
	v_mfma_f32_16x16x32_bf16 v[44:47], v[178:181], v[244:247], v[44:47]
	v_mfma_f32_16x16x32_bf16 v[16:19], v[178:181], v[248:251], v[16:19]
	v_mfma_f32_16x16x32_bf16 v[36:39], v[178:181], v[252:255], v[36:39]
	v_add3_u32 v128, s28, v150, v151
	ds_read_b128 v[178:181], v128 offset:32768
	v_add3_u32 v161, s28, v150, v152
	v_add3_u32 v194, s28, v154, v153
	v_add3_u32 v195, s28, v154, v155
	v_add3_u32 v196, s28, v154, v156
	ds_read_b128 v[162:165], v161
	ds_read_b128 v[166:169], v194
	ds_read_b128 v[170:173], v195
	ds_read_b128 v[174:177], v196
	s_cmpk_eq_i32 s12, 0x1500
	s_cbranch_scc1 .Lpk_1138_0
	s_mov_b32 m0, s101
	v_lshl_add_u64 v[146:147], v[146:147], 0, s[98:99]
	global_load_lds_dwordx4 v[146:147], off
.Lpk_1138_0:
	v_mfma_f32_16x16x32_bf16 v[56:59], v[182:185], v[240:243], v[56:59]
	v_mfma_f32_16x16x32_bf16 v[40:43], v[182:185], v[244:247], v[40:43]
	v_mfma_f32_16x16x32_bf16 v[8:11], v[182:185], v[248:251], v[8:11]
	v_mfma_f32_16x16x32_bf16 v[28:31], v[182:185], v[252:255], v[28:31]
	ds_read_b128 v[182:185], v128 offset:34816
	v_add3_u32 v197, s28, v154, v157
	v_add3_u32 v198, s28, v154, v158
	v_add3_u32 v199, s28, v154, v159
	v_add3_u32 v200, s28, v154, v160
	s_cmpk_eq_i32 s12, 0x1500
	s_cbranch_scc1 .Lpk_1138_1
	s_add_i32 m0, s101, 0x8000
	v_lshl_add_u64 v[138:139], v[138:139], 0, s[98:99]
	global_load_lds_dwordx4 v[138:139], off
.Lpk_1138_1:
	v_mfma_f32_16x16x32_bf16 v[52:55], v[186:189], v[240:243], v[52:55]
	v_mfma_f32_16x16x32_bf16 v[32:35], v[186:189], v[244:247], v[32:35]
	v_mfma_f32_16x16x32_bf16 v[4:7], v[186:189], v[248:251], v[4:7]
	v_mfma_f32_16x16x32_bf16 v[20:23], v[186:189], v[252:255], v[20:23]
	ds_read_b128 v[186:189], v128 offset:36864
	s_cmpk_eq_i32 s12, 0x1500
	s_cbranch_scc1 .Lpk_1138_2
	s_add_i32 m0, s101, 0x2000
	v_lshl_add_u64 v[144:145], v[144:145], 0, s[98:99]
	global_load_lds_dwordx4 v[144:145], off
.Lpk_1138_2:
	v_mfma_f32_16x16x32_bf16 v[48:51], v[190:193], v[240:243], v[48:51]
	v_mfma_f32_16x16x32_bf16 v[24:27], v[190:193], v[244:247], v[24:27]
	v_mfma_f32_16x16x32_bf16 v[0:3], v[190:193], v[248:251], v[0:3]
	v_mfma_f32_16x16x32_bf16 v[12:15], v[190:193], v[252:255], v[12:15]
	ds_read_b128 v[190:193], v128 offset:38912
	s_cmpk_eq_i32 s12, 0x1500
	s_cbranch_scc1 .Lpk_1138_3
	s_add_i32 m0, s101, 0xa000
	v_lshl_add_u64 v[136:137], v[136:137], 0, s[98:99]
	global_load_lds_dwordx4 v[136:137], off
